# thin-phase unit tops: no vmcnt(0) before the workgroup barrier (the previous unit's stores are covered in order by the unit's first counted wait)
# baseline (speedup 1.0000x reference)
.LBB0_454:
	s_lshl_b32 s10, s12, 4
	s_lshl_b32 s13, s12, 6
	s_and_b32 s10, s10, 0xfffff000
	s_and_b32 s13, s13, 0xfc0
	s_or_b32 s13, s10, s13
	s_nop 0
	s_barrier
	s_and_saveexec_b64 s[14:15], s[0:1]
	s_cbranch_execz .LBB0_456
	v_or_b32_e32 v4, s13, v48
	v_mov_b64_e32 v[2:3], s[8:9]
	v_mad_i64_i32 v[2:3], s[16:17], v4, s22, v[2:3]
	v_mov_b32_e32 v23, v11
	v_lshl_add_u64 v[2:3], v[2:3], 0, v[22:23]
	v_add_co_u32_e32 v2, vcc, 0xc000, v2
	s_nop 1
	v_addc_co_u32_e32 v3, vcc, 0, v3, vcc
	global_load_dwordx4 v[2:5], v[2:3], off offset:2560
	s_waitcnt vmcnt(0)
	v_lshlrev_b32_e32 v6, 16, v2
	v_and_b32_e32 v7, 0xffff0000, v2
	v_lshlrev_b32_e32 v8, 16, v3
	v_and_b32_e32 v9, 0xffff0000, v3
	v_lshlrev_b32_e32 v2, 16, v4
	v_and_b32_e32 v3, 0xffff0000, v4
	v_lshlrev_b32_e32 v4, 16, v5
	v_and_b32_e32 v5, 0xffff0000, v5
	ds_write_b128 v50, v[6:9]
	ds_write_b128 v50, v[2:5] offset:16

.LBB0_575:
	s_and_b32 s2, s36, 0xfffff000
	s_and_b32 s22, s38, 0xfc0
	s_or_b32 s46, s2, s22
	s_bfe_u32 s47, s45, 0x20006
	v_or_b32_e32 v4, s46, v1
	v_mov_b64_e32 v[6:7], s[0:1]
	v_mad_i64_i32 v[8:9], s[22:23], v4, s40, v[6:7]
	s_lshl_b32 s30, s47, 8
	s_mov_b32 s31, s3
	v_lshl_add_u64 v[8:9], v[8:9], 0, s[30:31]
	s_lshl_b32 s2, s47, 9
	v_ashrrev_i32_e32 v5, 31, v4
	v_lshl_add_u64 v[8:9], v[8:9], 0, v[74:75]
	v_lshl_add_u64 v[2:3], v[76:77], 0, s[2:3]
	v_add_co_u32_e32 v8, vcc, s41, v8
	v_lshlrev_b64 v[4:5], 11, v[4:5]
	s_nop 0
	v_addc_co_u32_e32 v9, vcc, 0, v9, vcc
	v_lshl_add_u64 v[4:5], v[2:3], 0, v[4:5]
	s_nop 0
	s_barrier
	global_load_dwordx4 v[140:143], v[8:9], off
	global_load_dwordx4 v[144:147], v[8:9], off offset:1024
	global_load_dwordx4 v[148:151], v[4:5], off offset:16
	global_load_dwordx4 v[152:155], v[4:5], off
	v_or_b32_e32 v4, s46, v106
	v_mad_i64_i32 v[8:9], s[22:23], v4, s40, v[6:7]
	v_lshl_add_u64 v[8:9], v[8:9], 0, s[30:31]
	v_ashrrev_i32_e32 v5, 31, v4
	v_lshl_add_u64 v[8:9], v[8:9], 0, v[74:75]
	v_add_co_u32_e32 v8, vcc, s41, v8
	v_lshlrev_b64 v[4:5], 11, v[4:5]
	s_nop 0
	v_addc_co_u32_e32 v9, vcc, 0, v9, vcc
	v_lshl_add_u64 v[2:3], v[2:3], 0, v[4:5]
	global_load_dwordx4 v[58:61], v[8:9], off
	global_load_dwordx4 v[46:49], v[8:9], off offset:1024
	global_load_dwordx4 v[54:57], v[2:3], off offset:16
	global_load_dwordx4 v[70:73], v[2:3], off
	v_or_b32_e32 v2, s46, v193
	v_mad_i64_i32 v[2:3], s[22:23], v2, s40, v[6:7]
	v_lshl_add_u64 v[2:3], v[2:3], 0, s[2:3]
	v_mov_b32_e32 v87, v75
	v_or_b32_e32 v4, s46, v107
	v_lshl_add_u64 v[2:3], v[2:3], 0, v[86:87]
	v_mad_i64_i32 v[4:5], s[22:23], v4, s40, v[6:7]
	v_add_co_u32_e32 v2, vcc, s41, v2
	v_lshl_add_u64 v[4:5], v[4:5], 0, s[2:3]
	s_nop 0
	v_addc_co_u32_e32 v3, vcc, 0, v3, vcc
	v_lshl_add_u64 v[4:5], v[4:5], 0, v[86:87]
	v_add_co_u32_e32 v4, vcc, s41, v4
	v_mov_b32_e32 v89, v75
	s_nop 0
	v_addc_co_u32_e32 v5, vcc, 0, v5, vcc
	global_load_dwordx4 v[42:45], v[2:3], off offset:2048
	global_load_dwordx4 v[50:53], v[4:5], off offset:2048
	v_or_b32_e32 v2, s46, v108
	v_mad_i64_i32 v[2:3], s[22:23], v2, s40, v[6:7]
	v_lshl_add_u64 v[2:3], v[2:3], 0, s[2:3]
	v_or_b32_e32 v4, s46, v109
	v_lshl_add_u64 v[2:3], v[2:3], 0, v[86:87]
	v_mad_i64_i32 v[4:5], s[22:23], v4, s40, v[6:7]
	v_add_co_u32_e32 v2, vcc, s41, v2
	v_lshl_add_u64 v[4:5], v[4:5], 0, s[2:3]
	s_nop 0
	v_addc_co_u32_e32 v3, vcc, 0, v3, vcc
	v_lshl_add_u64 v[4:5], v[4:5], 0, v[86:87]
	v_add_co_u32_e32 v4, vcc, s41, v4
	v_or_b32_e32 v87, s46, v110
	s_nop 0
	v_addc_co_u32_e32 v5, vcc, 0, v5, vcc
	global_load_dwordx4 v[62:65], v[2:3], off offset:2048
	global_load_dwordx4 v[66:69], v[4:5], off offset:2048
	v_lshl_add_u64 v[2:3], v[82:83], 0, v[80:81]
	v_lshl_add_u64 v[4:5], v[82:83], 0, v[84:85]
	global_load_dwordx4 v[34:37], v[2:3], off offset:-128
	global_load_dwordx4 v[26:29], v[2:3], off offset:-64
	global_load_dwordx4 v[38:41], v[4:5], off offset:-128
	global_load_dwordx4 v[30:33], v[4:5], off offset:-64
	global_load_dwordx4 v[18:21], v[2:3], off
	global_load_dwordx4 v[14:17], v[2:3], off offset:64
	global_load_dwordx4 v[22:25], v[4:5], off
	global_load_dwordx4 v[10:13], v[4:5], off offset:64
	v_mad_i64_i32 v[2:3], s[22:23], v87, s40, v[6:7]
	v_lshl_add_u64 v[2:3], v[2:3], 0, s[2:3]
	v_lshl_add_u64 v[2:3], v[2:3], 0, v[88:89]
	s_lshl_b32 s22, s47, 10
	s_mov_b32 s23, s3
	v_lshl_add_u64 v[90:91], v[2:3], 0, s[26:27]
	v_add_co_u32_e32 v92, vcc, s42, v2
	v_or_b32_e32 v2, 16, v87
	v_lshl_add_u64 v[4:5], v[78:79], 0, s[22:23]
	v_addc_co_u32_e32 v93, vcc, 0, v3, vcc
	v_mad_i64_i32 v[2:3], s[22:23], v2, s40, v[6:7]
	v_lshl_add_u64 v[2:3], v[2:3], 0, s[2:3]
	v_lshl_add_u64 v[2:3], v[2:3], 0, v[88:89]
	v_lshl_add_u64 v[94:95], v[2:3], 0, s[26:27]
	v_add_co_u32_e32 v96, vcc, s42, v2
	v_or_b32_e32 v2, 32, v87
	s_nop 0
	v_addc_co_u32_e32 v97, vcc, 0, v3, vcc
	v_mad_i64_i32 v[2:3], s[22:23], v2, s40, v[6:7]
	v_lshl_add_u64 v[2:3], v[2:3], 0, s[2:3]
	v_lshl_add_u64 v[2:3], v[2:3], 0, v[88:89]
	v_lshl_add_u64 v[156:157], v[2:3], 0, s[26:27]
	v_add_co_u32_e32 v158, vcc, s42, v2
	v_or_b32_e32 v2, 48, v87
	s_nop 0
	v_addc_co_u32_e32 v159, vcc, 0, v3, vcc
	v_mad_i64_i32 v[2:3], s[22:23], v2, s40, v[6:7]
	v_lshl_add_u64 v[2:3], v[2:3], 0, s[2:3]
	v_lshl_add_u64 v[2:3], v[2:3], 0, v[88:89]
	v_add_co_u32_e32 v162, vcc, s42, v2
	s_waitcnt vmcnt(16)
	v_mul_f32_e32 v89, 0x3fb8aa3b, v152
	v_lshl_add_u64 v[160:161], v[2:3], 0, s[26:27]
	v_addc_co_u32_e32 v163, vcc, 0, v3, vcc
	global_load_dwordx4 v[6:9], v[4:5], off
	s_nop 0
	global_load_dwordx4 v[2:5], v[4:5], off offset:64
	s_nop 0
	global_load_dwordx2 v[104:105], v[92:93], off
	global_load_dwordx2 v[100:101], v[96:97], off
	global_load_dwordx2 v[98:99], v[94:95], off offset:32
	global_load_dwordx2 v[102:103], v[90:91], off offset:32
	s_nop 0
	global_load_dwordx2 v[96:97], v[158:159], off
	global_load_dwordx2 v[92:93], v[162:163], off
	global_load_dwordx2 v[90:91], v[160:161], off offset:32
	global_load_dwordx2 v[94:95], v[156:157], off offset:32
	v_exp_f32_e32 v156, v89
	v_mul_f32_e32 v89, 0xbfb8aa3b, v152
	v_mul_f32_e32 v152, 0x3fb8aa3b, v153
	v_exp_f32_e32 v157, v152
	v_exp_f32_e32 v152, v89
	v_mul_f32_e32 v89, 0xbfb8aa3b, v153
	v_exp_f32_e32 v153, v89
	v_lshlrev_b32_e32 v158, 16, v140
	v_and_b32_e32 v159, 0xffff0000, v140
	v_pk_mul_f32 v[156:157], v[156:157], s[28:29] op_sel_hi:[1,0]
	v_mul_f32_e32 v89, 0x3fb8aa3b, v154
	v_pk_mul_f32 v[156:157], v[156:157], v[158:159]
	v_lshlrev_b32_e32 v158, 16, v144
	v_and_b32_e32 v159, 0xffff0000, v144
	v_pk_mul_f32 v[152:153], v[152:153], v[158:159]
	v_exp_f32_e32 v158, v89
	v_mul_f32_e32 v89, 0xbfb8aa3b, v154
	v_mul_f32_e32 v140, 0x3fb8aa3b, v155
	v_exp_f32_e32 v159, v140
	v_exp_f32_e32 v140, v89
	v_mul_f32_e32 v89, 0xbfb8aa3b, v155
	v_lshlrev_b32_e32 v160, 16, v141
	v_and_b32_e32 v161, 0xffff0000, v141
	v_exp_f32_e32 v141, v89
	v_lshlrev_b32_e32 v144, 16, v145
	v_and_b32_e32 v145, 0xffff0000, v145
	v_mul_f32_e32 v89, 0x3fb8aa3b, v148
	v_pk_mul_f32 v[144:145], v[140:141], v[144:145]
	v_mul_f32_e32 v141, 0x3fb8aa3b, v149
	v_exp_f32_e32 v140, v89
	v_mul_f32_e32 v89, 0xbfb8aa3b, v148
	v_exp_f32_e32 v141, v141
	v_exp_f32_e32 v148, v89
	v_mul_f32_e32 v89, 0xbfb8aa3b, v149
	v_exp_f32_e32 v149, v89
	v_pk_mul_f32 v[158:159], v[158:159], s[28:29] op_sel_hi:[1,0]
	v_pk_mul_f32 v[140:141], v[140:141], s[28:29] op_sel_hi:[1,0]
	v_pk_mul_f32 v[154:155], v[158:159], v[160:161]
	v_lshlrev_b32_e32 v158, 16, v142
	v_and_b32_e32 v159, 0xffff0000, v142
	v_pk_mul_f32 v[158:159], v[140:141], v[158:159]
	v_lshlrev_b32_e32 v140, 16, v146
	v_and_b32_e32 v141, 0xffff0000, v146
	v_pk_mul_f32 v[148:149], v[148:149], v[140:141]
	v_mul_f32_e32 v89, 0x3fb8aa3b, v150
	v_mul_f32_e32 v141, 0x3fb8aa3b, v151
	v_exp_f32_e32 v140, v89
	v_mul_f32_e32 v89, 0xbfb8aa3b, v150
	v_exp_f32_e32 v141, v141
	v_exp_f32_e32 v142, v89
	v_mul_f32_e32 v89, 0xbfb8aa3b, v151
	v_lshlrev_b32_e32 v160, 16, v143
	v_and_b32_e32 v161, 0xffff0000, v143
	v_exp_f32_e32 v143, v89
	v_pk_mul_f32 v[140:141], v[140:141], s[28:29] op_sel_hi:[1,0]
	s_waitcnt vmcnt(22)
	v_mul_f32_e32 v89, 0x3fb8aa3b, v70
	v_pk_mul_f32 v[150:151], v[140:141], v[160:161]
	v_lshlrev_b32_e32 v140, 16, v147
	v_and_b32_e32 v141, 0xffff0000, v147
	v_pk_mul_f32 v[146:147], v[142:143], v[140:141]
	v_cvt_pk_bf16_f32 v140, v156, v157
	v_cvt_pk_bf16_f32 v141, v154, v155
	v_cvt_pk_bf16_f32 v142, v158, v159
	v_cvt_pk_bf16_f32 v143, v150, v151
	ds_write_b128 v111, v[140:143]
	v_cvt_pk_bf16_f32 v140, v152, v153
	v_cvt_pk_bf16_f32 v141, v144, v145
	v_cvt_pk_bf16_f32 v142, v148, v149
	v_cvt_pk_bf16_f32 v143, v146, v147
	ds_write_b128 v111, v[140:143] offset:17408
	v_exp_f32_e32 v140, v89
	v_mul_f32_e32 v89, 0x3fb8aa3b, v71
	v_exp_f32_e32 v141, v89
	v_mul_f32_e32 v70, 0xbfb8aa3b, v70
	v_lshlrev_b32_e32 v142, 16, v58
	v_and_b32_e32 v143, 0xffff0000, v58
	v_mul_f32_e32 v58, 0xbfb8aa3b, v71
	v_exp_f32_e32 v70, v70
	v_exp_f32_e32 v71, v58
	v_pk_mul_f32 v[140:141], v[140:141], s[28:29] op_sel_hi:[1,0]
	v_mul_f32_e32 v58, 0x3fb8aa3b, v73
	v_pk_mul_f32 v[140:141], v[140:141], v[142:143]
	v_lshlrev_b32_e32 v142, 16, v46
	v_and_b32_e32 v143, 0xffff0000, v46
	v_mul_f32_e32 v46, 0x3fb8aa3b, v72
	v_pk_mul_f32 v[70:71], v[70:71], v[142:143]
	v_exp_f32_e32 v142, v46
	v_mul_f32_e32 v46, 0xbfb8aa3b, v72
	v_exp_f32_e32 v143, v58
	v_exp_f32_e32 v58, v46
	v_mul_f32_e32 v46, 0xbfb8aa3b, v73
	v_lshlrev_b32_e32 v144, 16, v59
	v_and_b32_e32 v145, 0xffff0000, v59
	v_exp_f32_e32 v59, v46
	v_lshlrev_b32_e32 v46, 16, v47
	v_and_b32_e32 v47, 0xffff0000, v47
	v_pk_mul_f32 v[142:143], v[142:143], s[28:29] op_sel_hi:[1,0]
	v_pk_mul_f32 v[58:59], v[58:59], v[46:47]
	v_mul_f32_e32 v46, 0x3fb8aa3b, v54
	v_mul_f32_e32 v47, 0x3fb8aa3b, v55
	v_exp_f32_e32 v46, v46
	v_exp_f32_e32 v47, v47
	v_mul_f32_e32 v54, 0xbfb8aa3b, v54
	v_mul_f32_e32 v55, 0xbfb8aa3b, v55
	v_exp_f32_e32 v54, v54
	v_exp_f32_e32 v55, v55
	v_pk_mul_f32 v[72:73], v[142:143], v[144:145]
	v_lshlrev_b32_e32 v142, 16, v60
	v_and_b32_e32 v143, 0xffff0000, v60
	v_pk_mul_f32 v[46:47], v[46:47], s[28:29] op_sel_hi:[1,0]
	v_lshlrev_b32_e32 v60, 16, v61
	v_pk_mul_f32 v[142:143], v[46:47], v[142:143]
	v_lshlrev_b32_e32 v46, 16, v48
	v_and_b32_e32 v47, 0xffff0000, v48
	v_pk_mul_f32 v[54:55], v[54:55], v[46:47]
	v_mul_f32_e32 v46, 0x3fb8aa3b, v56
	v_mul_f32_e32 v47, 0x3fb8aa3b, v57
	v_exp_f32_e32 v46, v46
	v_mul_f32_e32 v48, 0xbfb8aa3b, v56
	v_exp_f32_e32 v47, v47
	v_exp_f32_e32 v56, v48
	v_mul_f32_e32 v48, 0xbfb8aa3b, v57
	v_exp_f32_e32 v57, v48
	v_and_b32_e32 v61, 0xffff0000, v61
	v_pk_mul_f32 v[46:47], v[46:47], s[28:29] op_sel_hi:[1,0]
	v_cvt_pk_bf16_f32 v48, v142, v143
	v_pk_mul_f32 v[60:61], v[46:47], v[60:61]
	v_lshlrev_b32_e32 v46, 16, v49
	v_and_b32_e32 v47, 0xffff0000, v49
	v_pk_mul_f32 v[56:57], v[56:57], v[46:47]
	v_cvt_pk_bf16_f32 v46, v140, v141
	v_cvt_pk_bf16_f32 v47, v72, v73
	v_cvt_pk_bf16_f32 v49, v60, v61
	ds_write_b128 v112, v[46:49]
	v_cvt_pk_bf16_f32 v46, v70, v71
	v_cvt_pk_bf16_f32 v47, v58, v59
	v_cvt_pk_bf16_f32 v48, v54, v55
	v_cvt_pk_bf16_f32 v49, v56, v57
	ds_write_b128 v112, v[46:49] offset:17408
	s_waitcnt vmcnt(21)
	ds_write_b128 v127, v[42:45] offset:34816
	s_waitcnt vmcnt(20)
	ds_write_b128 v128, v[50:53] offset:34816
	s_waitcnt vmcnt(19)
	ds_write_b128 v127, v[62:65] offset:51712
	s_waitcnt vmcnt(18)
	ds_write_b128 v129, v[66:69] offset:34816
	s_waitcnt lgkmcnt(0)
	s_barrier
	ds_read_b128 v[42:45], v130
	ds_read_b128 v[46:49], v131 offset:17408
	ds_read_b128 v[50:53], v130 offset:64
	ds_read_b128 v[54:57], v131 offset:17472
	s_waitcnt lgkmcnt(2)
	v_mfma_f32_16x16x32_bf16 v[46:49], v[42:45], v[46:49], 0
	ds_read_b128 v[58:61], v131 offset:21760
	ds_read_b128 v[62:65], v131 offset:21824
	s_waitcnt lgkmcnt(2)
	v_mfma_f32_16x16x32_bf16 v[46:49], v[50:53], v[54:57], v[46:49]
	ds_read_b128 v[54:57], v130 offset:128
	s_waitcnt lgkmcnt(2)
	v_mfma_f32_16x16x32_bf16 v[42:45], v[42:45], v[58:61], 0
	s_waitcnt lgkmcnt(1)
	v_mfma_f32_16x16x32_bf16 v[42:45], v[50:53], v[62:65], v[42:45]
	ds_read_b128 v[50:53], v131 offset:17536
	ds_read_b128 v[58:61], v130 offset:192
	ds_read_b128 v[62:65], v131 offset:17600
	s_waitcnt lgkmcnt(2)
	v_mfma_f32_16x16x32_bf16 v[46:49], v[54:57], v[50:53], v[46:49]
	ds_read_b128 v[50:53], v131 offset:21888
	ds_read_b128 v[66:69], v131 offset:21952
	s_waitcnt lgkmcnt(2)
	v_mfma_f32_16x16x32_bf16 v[46:49], v[58:61], v[62:65], v[46:49]
	s_waitcnt lgkmcnt(1)
	v_mfma_f32_16x16x32_bf16 v[42:45], v[54:57], v[50:53], v[42:45]
	s_waitcnt lgkmcnt(0)
	v_mfma_f32_16x16x32_bf16 v[42:45], v[58:61], v[66:69], v[42:45]
	s_nop 3
	v_cndmask_b32_e64 v46, v46, 0, s[4:5]
	v_bfe_u32 v50, v46, 16, 1
	v_add3_u32 v46, v46, v50, s43
	ds_write_b16_d16_hi v132, v46
	v_cndmask_b32_e64 v46, v47, 0, s[6:7]
	v_bfe_u32 v47, v46, 16, 1
	v_add3_u32 v46, v46, v47, s43
	ds_write_b16_d16_hi v132, v46 offset:144
	v_cndmask_b32_e64 v46, v48, 0, s[8:9]
	v_bfe_u32 v47, v46, 16, 1
	v_add3_u32 v46, v46, v47, s43
	ds_write_b16_d16_hi v132, v46 offset:288
	v_cndmask_b32_e64 v46, v49, 0, s[10:11]
	v_bfe_u32 v47, v46, 16, 1
	v_add3_u32 v46, v46, v47, s43
	v_cndmask_b32_e64 v42, v42, 0, s[12:13]
	ds_write_b16_d16_hi v132, v46 offset:432
	v_bfe_u32 v46, v42, 16, 1
	v_add3_u32 v42, v42, v46, s43
	ds_write_b16_d16_hi v113, v42
	v_cndmask_b32_e64 v42, v43, 0, s[14:15]
	v_bfe_u32 v43, v42, 16, 1
	v_add3_u32 v42, v42, v43, s43
	ds_write_b16_d16_hi v114, v42
	v_cndmask_b32_e64 v42, v44, 0, s[16:17]
	v_bfe_u32 v43, v42, 16, 1
	v_add3_u32 v42, v42, v43, s43
	ds_write_b16_d16_hi v115, v42
	v_cndmask_b32_e64 v42, v45, 0, s[18:19]
	v_bfe_u32 v43, v42, 16, 1
	v_add3_u32 v42, v42, v43, s43
	ds_write_b16_d16_hi v116, v42
	s_waitcnt lgkmcnt(0)
	s_barrier
	ds_read_b128 v[42:45], v133
	ds_read_b128 v[46:49], v133 offset:64
	ds_read_b128 v[54:57], v133 offset:4352
	ds_read_b128 v[58:61], v133 offset:4416
	ds_read_b128 v[66:69], v133 offset:8704
	ds_read_b128 v[70:73], v133 offset:8768
	ds_read_b128 v[144:147], v133 offset:13056
	ds_read_b128 v[148:151], v133 offset:13120
	s_waitcnt vmcnt(17) lgkmcnt(7)
	v_mfma_f32_16x16x32_bf16 v[50:53], v[34:37], v[42:45], 0
	s_waitcnt vmcnt(15)
	v_mfma_f32_16x16x32_bf16 v[42:45], v[38:41], v[42:45], 0
	s_waitcnt lgkmcnt(5)
	v_mfma_f32_16x16x32_bf16 v[62:65], v[34:37], v[54:57], 0
	v_mfma_f32_16x16x32_bf16 v[54:57], v[38:41], v[54:57], 0
	s_waitcnt lgkmcnt(3)
	v_mfma_f32_16x16x32_bf16 v[140:143], v[34:37], v[66:69], 0
	v_mfma_f32_16x16x32_bf16 v[66:69], v[38:41], v[66:69], 0
	s_waitcnt lgkmcnt(1)
	v_mfma_f32_16x16x32_bf16 v[34:37], v[34:37], v[144:147], 0
	v_mfma_f32_16x16x32_bf16 v[38:41], v[38:41], v[144:147], 0
	v_mfma_f32_16x16x32_bf16 v[50:53], v[26:29], v[46:49], v[50:53]
	s_waitcnt vmcnt(14)
	v_mfma_f32_16x16x32_bf16 v[42:45], v[30:33], v[46:49], v[42:45]
	v_mfma_f32_16x16x32_bf16 v[46:49], v[26:29], v[58:61], v[62:65]
	v_mfma_f32_16x16x32_bf16 v[54:57], v[30:33], v[58:61], v[54:57]
	v_mfma_f32_16x16x32_bf16 v[58:61], v[26:29], v[70:73], v[140:143]
	v_mfma_f32_16x16x32_bf16 v[62:65], v[30:33], v[70:73], v[66:69]
	s_waitcnt lgkmcnt(0)
	v_mfma_f32_16x16x32_bf16 v[26:29], v[26:29], v[148:151], v[34:37]
	v_mfma_f32_16x16x32_bf16 v[30:33], v[30:33], v[148:151], v[38:41]
	s_nop 1
	ds_read_b128 v[34:37], v133 offset:128
	ds_read_b128 v[38:41], v133 offset:192
	s_waitcnt vmcnt(13) lgkmcnt(1)
	v_mfma_f32_16x16x32_bf16 v[50:53], v[18:21], v[34:37], v[50:53]
	s_waitcnt vmcnt(11)
	v_mfma_f32_16x16x32_bf16 v[34:37], v[22:25], v[34:37], v[42:45]
	s_nop 2
	ds_read_b128 v[42:45], v133 offset:4480
	ds_read_b128 v[66:69], v133 offset:4544
	s_waitcnt lgkmcnt(1)
	v_mfma_f32_16x16x32_bf16 v[46:49], v[18:21], v[42:45], v[46:49]
	v_mfma_f32_16x16x32_bf16 v[42:45], v[22:25], v[42:45], v[54:57]
	s_nop 2
	ds_read_b128 v[54:57], v133 offset:8832
	ds_read_b128 v[70:73], v133 offset:8896
	s_waitcnt lgkmcnt(1)
	v_mfma_f32_16x16x32_bf16 v[58:61], v[18:21], v[54:57], v[58:61]
	v_mfma_f32_16x16x32_bf16 v[54:57], v[22:25], v[54:57], v[62:65]
	s_nop 2
	ds_read_b128 v[62:65], v133 offset:13184
	ds_read_b128 v[140:143], v133 offset:13248
	s_waitcnt lgkmcnt(1)
	v_mfma_f32_16x16x32_bf16 v[18:21], v[18:21], v[62:65], v[26:29]
	v_mfma_f32_16x16x32_bf16 v[22:25], v[22:25], v[62:65], v[30:33]
	v_mfma_f32_16x16x32_bf16 v[26:29], v[14:17], v[38:41], v[50:53]
	s_waitcnt vmcnt(10)
	v_mfma_f32_16x16x32_bf16 v[30:33], v[10:13], v[38:41], v[34:37]
	v_mfma_f32_16x16x32_bf16 v[34:37], v[14:17], v[66:69], v[46:49]
	v_mfma_f32_16x16x32_bf16 v[38:41], v[10:13], v[66:69], v[42:45]
	v_mfma_f32_16x16x32_bf16 v[42:45], v[14:17], v[70:73], v[58:61]
	s_waitcnt lgkmcnt(0)
	v_mfma_f32_16x16x32_bf16 v[14:17], v[14:17], v[140:143], v[18:21]
	s_nop 2
	ds_read_b64_tr_b16 v[20:21], v134 offset:36928
	ds_read_b64_tr_b16 v[18:19], v134 offset:34816
	v_mfma_f32_16x16x32_bf16 v[46:49], v[10:13], v[70:73], v[54:57]
	v_mfma_f32_16x16x32_bf16 v[10:13], v[10:13], v[140:143], v[22:25]
	s_nop 2
	ds_read_b64_tr_b16 v[24:25], v134 offset:36960
	ds_read_b64_tr_b16 v[22:23], v134 offset:34848
	ds_read_b128 v[50:53], v135
	ds_read_b128 v[54:57], v135 offset:64
	s_waitcnt lgkmcnt(1)
	v_mfma_f32_16x16x32_bf16 v[26:29], v[18:21], v[50:53], v[26:29]
	v_mfma_f32_16x16x32_bf16 v[30:33], v[22:25], v[50:53], v[30:33]
	ds_read_b128 v[50:53], v135 offset:2304
	ds_read_b128 v[58:61], v135 offset:2368
	s_waitcnt lgkmcnt(1)
	v_mfma_f32_16x16x32_bf16 v[62:65], v[18:21], v[50:53], v[34:37]
	s_nop 2
	ds_read_b128 v[34:37], v135 offset:4608
	ds_read_b128 v[66:69], v135 offset:4672
	s_waitcnt lgkmcnt(1)
	v_mfma_f32_16x16x32_bf16 v[42:45], v[18:21], v[34:37], v[42:45]
	v_mfma_f32_16x16x32_bf16 v[46:49], v[22:25], v[34:37], v[46:49]
	ds_read_b128 v[34:37], v135 offset:6912
	ds_read_b128 v[70:73], v135 offset:6976
	ds_read_b64_tr_b16 v[140:141], v134 offset:51712
	ds_read_b64_tr_b16 v[142:143], v134 offset:53824
	ds_read_b64_tr_b16 v[150:151], v134 offset:53856
	ds_read_b64_tr_b16 v[148:149], v134 offset:51744
	s_waitcnt lgkmcnt(5)
	v_mfma_f32_16x16x32_bf16 v[14:17], v[18:21], v[34:37], v[14:17]
	v_mfma_f32_16x16x32_bf16 v[50:53], v[22:25], v[50:53], v[38:41]
	v_mfma_f32_16x16x32_bf16 v[144:147], v[22:25], v[34:37], v[10:13]
	s_waitcnt lgkmcnt(2)
	v_mfma_f32_16x16x32_bf16 v[38:41], v[140:143], v[54:57], v[26:29]
	v_mfma_f32_16x16x32_bf16 v[10:13], v[140:143], v[70:73], v[14:17]
	s_nop 2
	v_and_b32_e32 v15, 64, v138
	v_xor_b32_e32 v14, 16, v138
	v_add_u32_e32 v15, 64, v15
	v_cmp_lt_i32_e32 vcc, v14, v15
	s_waitcnt lgkmcnt(0)
	v_mfma_f32_16x16x32_bf16 v[34:37], v[148:151], v[54:57], v[30:33]
	v_xor_b32_e32 v17, 32, v138
	v_cndmask_b32_e32 v14, v138, v14, vcc
	v_cmp_lt_i32_e32 vcc, v17, v15
	v_mfma_f32_16x16x32_bf16 v[22:25], v[140:143], v[66:69], v[42:45]
	s_nop 0
	v_cndmask_b32_e32 v15, v138, v17, vcc
	s_nop 0
	v_lshlrev_b32_e32 v42, 2, v14
	v_mul_f32_e32 v14, v39, v39
	v_fmac_f32_e32 v14, v38, v38
	v_fmac_f32_e32 v14, v40, v40
	v_fmac_f32_e32 v14, v41, v41
	v_fmac_f32_e32 v14, v34, v34
	v_fmac_f32_e32 v14, v35, v35
	v_fmac_f32_e32 v14, v36, v36
	v_fmac_f32_e32 v14, v37, v37
	ds_bpermute_b32 v16, v42, v14
	v_lshlrev_b32_e32 v43, 2, v15
	v_mfma_f32_16x16x32_bf16 v[30:33], v[140:143], v[58:61], v[62:65]
	s_waitcnt lgkmcnt(0)
	v_add_f32_e32 v44, v14, v16
	ds_bpermute_b32 v45, v43, v44
	v_mfma_f32_16x16x32_bf16 v[26:29], v[148:151], v[58:61], v[50:53]
	v_mfma_f32_16x16x32_bf16 v[18:21], v[148:151], v[66:69], v[46:49]
	v_mfma_f32_16x16x32_bf16 v[14:17], v[148:151], v[70:73], v[144:147]
	s_and_saveexec_b64 s[22:23], s[20:21]
	s_cbranch_execz .LBB0_577
	s_waitcnt lgkmcnt(0)
	v_add_f32_e32 v44, v44, v45
	ds_write_b32 v139, v44

.LBB0_585:
	s_and_b32 s12, s27, 3
	s_lshl_b32 s4, 0xffffffc0, s12
	v_add_u32_e32 v2, s4, v1
	s_and_b32 s8, s17, 0xffffff80
	s_lshl_b32 s28, s27, 5
	s_lshl_b32 s2, s12, 9
	v_lshrrev_b32_e32 v2, 5, v2
	s_and_b32 s9, s28, 0xfffff000
	s_lshl_b32 s29, s12, 8
	v_lshl_add_u64 v[6:7], v[78:79], 0, s[2:3]
	v_add3_u32 v8, v2, s8, -15
	v_lshl_add_u32 v9, v2, 9, v106
	v_add_u32_e32 v10, s4, v0
	s_mov_b64 s[4:5], 0
	s_nop 0
	s_barrier
	s_branch .LBB0_587

.LBB0_622:
	v_readlane_b32 s0, v249, 34
	v_readlane_b32 s1, v249, 35
	v_writelane_b32 v249, s76, 48
	s_cmpk_lg_i32 s0, 0x100
	s_mov_b64 s[0:1], -1
	v_writelane_b32 v249, s77, 49
	s_nop 0
	s_barrier
	v_writelane_b32 v249, s75, 50
	s_cbranch_scc0 .LBB0_637
	s_cmpk_gt_i32 s76, 0x3ff
	s_cbranch_scc1 .LBB0_636
	v_mbcnt_lo_u32_b32 v1, -1, 0
	v_mbcnt_hi_u32_b32 v2, -1, v1
	v_readlane_b32 s43, v249, 45
	v_and_b32_e32 v3, 64, v2
	s_mul_i32 s0, s43, 0x1500
	v_xor_b32_e32 v1, 16, v2
	v_add_u32_e32 v3, 64, v3
	s_add_i32 s42, s0, 0
	v_cmp_lt_i32_e32 vcc, v1, v3
	v_xor_b32_e32 v4, 32, v2
	s_add_i32 s42, s42, 0x17a00
	s_lshl_b32 s33, s43, 4
	v_cndmask_b32_e32 v1, v2, v1, vcc
	v_cmp_lt_i32_e32 vcc, v4, v3
	s_add_u32 s2, s92, 0x3a000000
	s_movk_i32 s0, 0x200
	v_lshrrev_b32_e32 v3, 1, v0
	s_addc_u32 s3, s93, 0
	v_cmp_gt_u32_e64 s[4:5], s0, v0
	v_and_b32_e32 v14, 15, v0
	v_and_b32_e32 v15, 24, v3
	v_cndmask_b32_e32 v2, v2, v4, vcc
	s_add_u32 s44, s92, 0x100000
	v_writelane_b32 v249, s4, 55
	v_or_b32_e32 v44, s33, v14
	s_movk_i32 s0, 0x90
	v_lshlrev_b32_e32 v16, 1, v15
	v_lshlrev_b32_e32 v39, 2, v2
	s_addc_u32 s45, s93, 0
	v_writelane_b32 v249, s5, 56
	v_mul_lo_u32 v2, v44, s0
	v_add_u32_e32 v3, 0, v16
	s_add_i32 s4, s33, 16
	v_add_u32_e32 v45, v3, v2
	v_or_b32_e32 v2, s4, v14
	s_add_i32 s5, s33, 32
	v_mul_lo_u32 v4, v2, s0
	v_or_b32_e32 v2, s5, v14
	s_add_i32 s16, s33, 48
	v_mul_lo_u32 v5, v2, s0
	v_or_b32_e32 v2, s16, v14
	s_add_i32 s18, s33, 64
	v_mul_lo_u32 v6, v2, s0
	v_or_b32_e32 v2, s18, v14
	s_add_i32 s20, s33, 0x50
	v_mul_lo_u32 v7, v2, s0
	v_or_b32_e32 v2, s20, v14
	s_add_i32 s22, s33, 0x60
	v_mul_lo_u32 v8, v2, s0
	v_or_b32_e32 v2, s22, v14
	s_add_i32 s24, s33, 0x70
	v_mul_lo_u32 v9, v2, s0
	v_or_b32_e32 v2, s24, v14
	s_add_i32 s26, s33, 0x80
	v_mul_lo_u32 v10, v2, s0
	v_or_b32_e32 v2, s26, v14
	s_add_i32 s34, s33, 0x90
	v_mul_lo_u32 v11, v2, s0
	v_or_b32_e32 v2, s34, v14
	v_mul_lo_u32 v12, v2, s0
	v_lshrrev_b32_e32 v2, 2, v178
	v_and_b32_e32 v2, 12, v2
	v_add_u32_e32 v17, 0x80, v44
	v_or_b32_e32 v18, s33, v2
	v_cmp_gt_u32_e32 vcc, v2, v14
	v_cmp_le_u32_e64 s[8:9], v18, v17
	s_and_b64 s[8:9], vcc, s[8:9]
	v_cmp_ge_u32_e32 vcc, v2, v14
	v_writelane_b32 v249, s8, 57
	s_movk_i32 s25, 0x7e
	v_or_b32_e32 v19, 2, v18
	v_writelane_b32 v249, s9, 58
	v_cmp_le_u32_e64 s[10:11], v19, v17
	v_readlane_b32 s27, v249, 50
	s_cmpk_gt_u32 s27, 0x1ff
	s_cselect_b64 s[8:9], -1, 0
	v_writelane_b32 v249, s8, 59
	v_lshrrev_b32_e32 v47, 2, v0
	v_and_b32_e32 v13, 3, v0
	v_writelane_b32 v249, s9, 60
	v_cmp_lt_u32_e64 s[8:9], v18, v17
	s_and_b64 s[8:9], vcc, s[8:9]
	v_cmp_gt_u32_e32 vcc, v19, v44
	v_writelane_b32 v249, s8, 61
	v_lshlrev_b32_e32 v38, 4, v13
	v_cmp_eq_u32_e64 s[6:7], 0, v13
	v_writelane_b32 v249, s9, 62
	v_cmp_lt_u32_e64 s[8:9], s25, v18
	v_or_b32_e32 v18, 3, v18
	v_lshl_add_u32 v13, v13, 5, 0
	v_writelane_b32 v249, s8, 63
	v_mad_u32_u24 v53, v47, s0, 0
	s_mov_b32 s1, 0
	v_writelane_b32 v248, s9, 0
	s_and_b64 s[8:9], vcc, s[10:11]
	v_writelane_b32 v248, s8, 1
	v_cmp_gt_u32_e32 vcc, v18, v44
	v_cmp_le_u32_e64 s[10:11], v18, v17
	v_writelane_b32 v248, s9, 2
	s_and_b64 s[8:9], vcc, s[10:11]
	v_or_b32_e32 v18, s4, v2
	v_writelane_b32 v248, s8, 3
	v_cmp_gt_u32_e32 vcc, v18, v44
	v_cmp_le_u32_e64 s[10:11], v18, v17
	v_writelane_b32 v248, s9, 4
	s_and_b64 s[8:9], vcc, s[10:11]
	v_writelane_b32 v248, s8, 5
	s_cmpk_gt_u32 s27, 0x1bf
	v_cmp_ge_u32_e32 vcc, v18, v44
	v_writelane_b32 v248, s9, 6
	s_cselect_b64 s[8:9], -1, 0
	v_writelane_b32 v248, s8, 7
	v_cmp_lt_u32_e64 s[10:11], v18, v17
	v_or_b32_e32 v19, 2, v18
	v_writelane_b32 v248, s9, 8
	s_and_b64 s[8:9], vcc, s[10:11]
	v_writelane_b32 v248, s8, 9
	v_cmp_gt_u32_e32 vcc, v19, v44
	v_cmp_le_u32_e64 s[12:13], v19, v17
	v_writelane_b32 v248, s9, 10
	v_cmp_lt_u32_e64 s[8:9], s25, v18
	v_or_b32_e32 v18, 3, v18
	v_lshlrev_b32_e32 v1, 2, v1
	v_writelane_b32 v248, s8, 11
	v_mov_b32_e32 v41, 0
	v_or_b32_e32 v54, 0xffffff80, v47
	v_writelane_b32 v248, s9, 12
	s_and_b64 s[8:9], vcc, s[12:13]
	v_writelane_b32 v248, s8, 13
	v_cmp_gt_u32_e32 vcc, v18, v44
	v_cmp_le_u32_e64 s[12:13], v18, v17
	v_writelane_b32 v248, s9, 14
	s_and_b64 s[8:9], vcc, s[12:13]
	v_or_b32_e32 v18, s5, v2
	v_writelane_b32 v248, s8, 15
	v_cmp_gt_u32_e32 vcc, v18, v44
	v_cmp_le_u32_e64 s[12:13], v18, v17
	v_writelane_b32 v248, s9, 16
	s_and_b64 s[4:5], vcc, s[12:13]
	v_writelane_b32 v248, s4, 17
	s_cmpk_gt_u32 s27, 0x17f
	v_cmp_ge_u32_e32 vcc, v18, v44
	v_writelane_b32 v248, s5, 18
	s_cselect_b64 s[4:5], -1, 0
	v_writelane_b32 v248, s4, 19
	v_cmp_lt_u32_e64 s[12:13], v18, v17
	v_or_b32_e32 v19, 2, v18
	v_writelane_b32 v248, s5, 20
	s_and_b64 s[4:5], vcc, s[12:13]
	v_writelane_b32 v248, s4, 21
	v_cmp_gt_u32_e32 vcc, v19, v44
	v_cmp_le_u32_e64 s[14:15], v19, v17
	v_writelane_b32 v248, s5, 22
	v_cmp_lt_u32_e64 s[4:5], s25, v18
	v_or_b32_e32 v18, 3, v18
	s_movk_i32 s12, 0x150
	v_writelane_b32 v248, s4, 23
	s_mov_b32 s80, 0xcc00
	s_mov_b32 s72, 0x3e000000
	v_writelane_b32 v248, s5, 24
	s_and_b64 s[4:5], vcc, s[14:15]
	v_writelane_b32 v249, s4, 51
	v_cmp_gt_u32_e32 vcc, v18, v44
	v_cmp_le_u32_e64 s[14:15], v18, v17
	v_writelane_b32 v249, s5, 52
	s_and_b64 s[4:5], vcc, s[14:15]
	v_or_b32_e32 v18, s16, v2
	v_writelane_b32 v249, s4, 53
	v_cmp_gt_u32_e32 vcc, v18, v44
	v_cmp_le_u32_e64 s[14:15], v18, v17
	v_writelane_b32 v249, s5, 54
	s_and_b64 s[4:5], vcc, s[14:15]
	v_writelane_b32 v248, s4, 25
	s_cmpk_gt_u32 s27, 0x13f
	v_cmp_ge_u32_e32 vcc, v18, v44
	v_writelane_b32 v248, s5, 26
	s_cselect_b64 s[4:5], -1, 0
	v_writelane_b32 v248, s4, 27
	v_cmp_lt_u32_e64 s[14:15], v18, v17
	v_or_b32_e32 v19, 2, v18
	v_writelane_b32 v248, s5, 28
	s_and_b64 s[4:5], vcc, s[14:15]
	v_writelane_b32 v248, s4, 29
	v_cmp_gt_u32_e32 vcc, v19, v44
	v_cmp_le_u32_e64 s[16:17], v19, v17
	v_writelane_b32 v248, s5, 30
	v_cmp_lt_u32_e64 s[4:5], s25, v18
	v_or_b32_e32 v18, 3, v18
	v_add_u32_e32 v56, v3, v4
	v_writelane_b32 v248, s4, 31
	v_add_u32_e32 v57, v3, v5
	v_add_u32_e32 v58, v3, v6
	v_writelane_b32 v248, s5, 32
	s_and_b64 s[4:5], vcc, s[16:17]
	v_writelane_b32 v248, s4, 33
	v_cmp_gt_u32_e32 vcc, v18, v44
	v_cmp_le_u32_e64 s[16:17], v18, v17
	v_writelane_b32 v248, s5, 34
	s_and_b64 s[4:5], vcc, s[16:17]
	v_or_b32_e32 v18, s18, v2
	v_writelane_b32 v248, s4, 35
	v_cmp_gt_u32_e32 vcc, v18, v44
	v_cmp_le_u32_e64 s[16:17], v18, v17
	v_writelane_b32 v248, s5, 36
	s_and_b64 s[4:5], vcc, s[16:17]
	v_writelane_b32 v248, s4, 37
	s_cmpk_gt_u32 s27, 0xff
	v_cmp_ge_u32_e32 vcc, v18, v44
	v_writelane_b32 v248, s5, 38
	s_cselect_b64 s[4:5], -1, 0
	v_writelane_b32 v248, s4, 39
	v_cmp_lt_u32_e64 s[16:17], v18, v17
	v_or_b32_e32 v19, 2, v18
	v_writelane_b32 v248, s5, 40
	s_and_b64 s[4:5], vcc, s[16:17]
	v_writelane_b32 v248, s4, 41
	v_cmp_gt_u32_e32 vcc, v19, v44
	v_cmp_le_u32_e64 s[18:19], v19, v17
	v_writelane_b32 v248, s5, 42
	v_cmp_lt_u32_e64 s[4:5], s25, v18
	v_or_b32_e32 v18, 3, v18
	v_add_u32_e32 v59, v3, v7
	v_writelane_b32 v248, s4, 43
	v_add_u32_e32 v60, v3, v8
	v_add_u32_e32 v61, v3, v9
	v_writelane_b32 v248, s5, 44
	s_and_b64 s[4:5], vcc, s[18:19]
	v_writelane_b32 v248, s4, 45
	v_cmp_gt_u32_e32 vcc, v18, v44
	v_cmp_le_u32_e64 s[18:19], v18, v17
	v_writelane_b32 v248, s5, 46
	s_and_b64 s[4:5], vcc, s[18:19]
	v_or_b32_e32 v18, s20, v2
	v_writelane_b32 v248, s4, 47
	v_cmp_gt_u32_e32 vcc, v18, v44
	v_cmp_le_u32_e64 s[18:19], v18, v17
	v_writelane_b32 v248, s5, 48
	s_and_b64 s[4:5], vcc, s[18:19]
	v_writelane_b32 v248, s4, 49
	s_cmpk_gt_u32 s27, 0xbf
	v_cmp_ge_u32_e32 vcc, v18, v44
	v_cmp_lt_u32_e64 s[18:19], v18, v17
	v_or_b32_e32 v19, 2, v18
	v_writelane_b32 v248, s5, 50
	s_cselect_b64 s[86:87], -1, 0
	s_and_b64 s[88:89], vcc, s[18:19]
	v_cmp_lt_u32_e64 s[4:5], s25, v18
	v_cmp_gt_u32_e32 vcc, v19, v44
	v_cmp_le_u32_e64 s[20:21], v19, v17
	v_or_b32_e32 v18, 3, v18
	s_and_b64 s[8:9], vcc, s[20:21]
	v_cmp_gt_u32_e32 vcc, v18, v44
	v_cmp_le_u32_e64 s[20:21], v18, v17
	v_or_b32_e32 v18, s22, v2
	s_and_b64 s[90:91], vcc, s[20:21]
	v_cmp_gt_u32_e32 vcc, v18, v44
	v_cmp_le_u32_e64 s[20:21], v18, v17
	s_and_b64 s[16:17], vcc, s[20:21]
	v_writelane_b32 v248, s4, 51
	s_cmpk_gt_u32 s27, 0x7f
	v_cmp_ge_u32_e32 vcc, v18, v44
	v_cmp_lt_u32_e64 s[20:21], v18, v17
	v_or_b32_e32 v19, 2, v18
	v_writelane_b32 v248, s5, 52
	s_cselect_b64 s[96:97], -1, 0
	s_and_b64 s[4:5], vcc, s[20:21]
	v_cmp_lt_u32_e64 s[20:21], s25, v18
	v_cmp_gt_u32_e32 vcc, v19, v44
	v_cmp_le_u32_e64 s[22:23], v19, v17
	v_or_b32_e32 v18, 3, v18
	s_and_b64 s[46:47], vcc, s[22:23]
	v_cmp_gt_u32_e32 vcc, v18, v44
	v_cmp_le_u32_e64 s[22:23], v18, v17
	v_or_b32_e32 v18, s24, v2
	s_and_b64 s[10:11], vcc, s[22:23]
	v_cmp_gt_u32_e32 vcc, v18, v44
	v_cmp_le_u32_e64 s[22:23], v18, v17
	s_and_b64 s[18:19], vcc, s[22:23]
	s_cmp_gt_u32 s27, 63
	v_cmp_ge_u32_e32 vcc, v18, v44
	v_cmp_lt_u32_e64 s[22:23], v18, v17
	v_or_b32_e32 v19, 2, v18
	s_cselect_b64 s[64:65], -1, 0
	s_and_b64 s[66:67], vcc, s[22:23]
	v_cmp_lt_u32_e64 s[22:23], s25, v18
	v_cmp_gt_u32_e32 vcc, v19, v44
	v_cmp_le_u32_e64 s[24:25], v19, v17
	v_or_b32_e32 v18, 3, v18
	s_and_b64 s[68:69], vcc, s[24:25]
	v_cmp_gt_u32_e32 vcc, v18, v44
	v_cmp_le_u32_e64 s[24:25], v18, v17
	v_or_b32_e32 v18, s26, v2
	s_and_b64 s[70:71], vcc, s[24:25]
	v_cmp_gt_u32_e32 vcc, v18, v44
	v_cmp_le_u32_e64 s[24:25], v18, v17
	s_and_b64 s[24:25], vcc, s[24:25]
	v_cmp_ge_u32_e32 vcc, v18, v44
	v_cmp_lt_u32_e64 s[26:27], v18, v17
	v_or_b32_e32 v19, 2, v18
	s_and_b64 s[26:27], vcc, s[26:27]
	v_cmp_gt_u32_e32 vcc, v19, v44
	v_cmp_le_u32_e64 s[28:29], v19, v17
	v_or_b32_e32 v18, 3, v18
	s_and_b64 s[28:29], vcc, s[28:29]
	v_cmp_gt_u32_e32 vcc, v18, v44
	v_cmp_le_u32_e64 s[30:31], v18, v17
	v_or_b32_e32 v18, s34, v2
	s_and_b64 s[30:31], vcc, s[30:31]
	v_cmp_gt_u32_e32 vcc, v18, v44
	v_cmp_le_u32_e64 s[34:35], v18, v17
	s_and_b64 s[34:35], vcc, s[34:35]
	v_cmp_ge_u32_e32 vcc, v18, v44
	v_cmp_lt_u32_e64 s[36:37], v18, v17
	v_or_b32_e32 v19, 2, v18
	s_and_b64 s[36:37], vcc, s[36:37]
	v_cmp_gt_u32_e32 vcc, v19, v44
	v_cmp_le_u32_e64 s[38:39], v19, v17
	v_or_b32_e32 v18, 3, v18
	s_and_b64 s[38:39], vcc, s[38:39]
	v_cmp_gt_u32_e32 vcc, v18, v44
	v_cmp_le_u32_e64 s[40:41], v18, v17
	v_mov_b32_e32 v17, s42
	s_and_b64 s[40:41], vcc, s[40:41]
	v_mad_u32_u24 v14, v14, s12, v17
	v_lshl_add_u32 v46, v2, 1, v14
	v_add_u32_e32 v48, v14, v16
	v_add_u32_e32 v14, s33, v15
	s_add_u32 s12, s92, 0xf000000
	v_and_or_b32 v14, v47, 3, v14
	s_addc_u32 s13, s93, 0
	s_lshl_b32 s14, s43, 11
	v_lshlrev_b32_e32 v15, 1, v195
	v_mul_lo_u32 v14, v14, s0
	s_and_b32 s33, s14, 0x3800
	v_readlane_b32 s14, v249, 48
	v_add3_u32 v49, 0, v15, v14
	v_lshrrev_b32_e32 v14, 1, v178
	v_readlane_b32 s15, v249, 49
	v_mul_u32_u24_e32 v17, 0x90, v47
	v_and_b32_e32 v14, 24, v14
	s_mov_b32 s0, s14
	s_lshl_b32 s78, s14, 3
	v_readlane_b32 s14, v249, 34
	v_add_u32_e32 v50, 0xe100, v49
	v_or_b32_e32 v51, s33, v14
	v_or_b32_e32 v52, 32, v14
	s_or_b32 s73, s33, 0x400
	s_lshl_b32 s79, s14, 3
	v_add_u32_e32 v55, v13, v17
	v_add_u32_e32 v62, v3, v10
	v_add_u32_e32 v63, v3, v11
	v_add_u32_e32 v64, v3, v12
	v_lshlrev_b32_e32 v42, 1, v2
	v_mov_b32_e32 v65, 0xff800000
	s_mov_b32 s81, s0
	s_mov_b32 s14, s0
	v_readlane_b32 s15, v249, 35
	s_branch .LBB0_626

.LBB0_1237:
	s_lshl_b32 s10, s12, 4
	s_lshl_b32 s13, s12, 6
	s_and_b32 s10, s10, 0xfffff000
	s_and_b32 s13, s13, 0xfc0
	s_or_b32 s13, s10, s13
	s_nop 0
	s_barrier
	s_and_saveexec_b64 s[14:15], s[4:5]
	s_cbranch_execz .LBB0_1239
	v_or_b32_e32 v4, s13, v47
	v_mov_b64_e32 v[2:3], s[2:3]
	v_mad_i64_i32 v[2:3], s[16:17], v4, s23, v[2:3]
	v_mov_b32_e32 v23, v11
	v_lshl_add_u64 v[2:3], v[2:3], 0, v[22:23]
	v_add_co_u32_e32 v2, vcc, 0xc000, v2
	s_nop 1
	v_addc_co_u32_e32 v3, vcc, 0, v3, vcc
	global_load_dwordx4 v[2:5], v[2:3], off offset:2560
	s_waitcnt vmcnt(0)
	v_lshlrev_b32_e32 v6, 16, v2
	v_and_b32_e32 v7, 0xffff0000, v2
	v_lshlrev_b32_e32 v8, 16, v3
	v_and_b32_e32 v9, 0xffff0000, v3
	v_lshlrev_b32_e32 v2, 16, v4
	v_and_b32_e32 v3, 0xffff0000, v4
	v_lshlrev_b32_e32 v4, 16, v5
	v_and_b32_e32 v5, 0xffff0000, v5
	ds_write_b128 v49, v[6:9]
	ds_write_b128 v49, v[2:5] offset:16

.LBB0_1358:
	s_and_b32 s2, s36, 0xfffff000
	s_and_b32 s22, s38, 0xfc0
	s_or_b32 s46, s2, s22
	s_bfe_u32 s47, s45, 0x20006
	v_or_b32_e32 v4, s46, v106
	v_mov_b64_e32 v[6:7], s[0:1]
	v_mad_i64_i32 v[8:9], s[22:23], v4, s40, v[6:7]
	s_lshl_b32 s30, s47, 8
	s_mov_b32 s31, s3
	v_lshl_add_u64 v[8:9], v[8:9], 0, s[30:31]
	s_lshl_b32 s2, s47, 9
	v_ashrrev_i32_e32 v5, 31, v4
	v_lshl_add_u64 v[8:9], v[8:9], 0, v[74:75]
	v_lshl_add_u64 v[2:3], v[76:77], 0, s[2:3]
	v_add_co_u32_e32 v8, vcc, s41, v8
	v_lshlrev_b64 v[4:5], 11, v[4:5]
	s_nop 0
	v_addc_co_u32_e32 v9, vcc, 0, v9, vcc
	v_lshl_add_u64 v[4:5], v[2:3], 0, v[4:5]
	s_nop 0
	s_barrier
	global_load_dwordx4 v[142:145], v[8:9], off
	global_load_dwordx4 v[146:149], v[8:9], off offset:1024
	global_load_dwordx4 v[150:153], v[4:5], off offset:16
	global_load_dwordx4 v[154:157], v[4:5], off
	v_or_b32_e32 v4, s46, v107
	v_mad_i64_i32 v[8:9], s[22:23], v4, s40, v[6:7]
	v_lshl_add_u64 v[8:9], v[8:9], 0, s[30:31]
	v_ashrrev_i32_e32 v5, 31, v4
	v_lshl_add_u64 v[8:9], v[8:9], 0, v[74:75]
	v_add_co_u32_e32 v8, vcc, s41, v8
	v_lshlrev_b64 v[4:5], 11, v[4:5]
	s_nop 0
	v_addc_co_u32_e32 v9, vcc, 0, v9, vcc
	v_lshl_add_u64 v[2:3], v[2:3], 0, v[4:5]
	global_load_dwordx4 v[58:61], v[8:9], off
	global_load_dwordx4 v[46:49], v[8:9], off offset:1024
	global_load_dwordx4 v[54:57], v[2:3], off offset:16
	global_load_dwordx4 v[70:73], v[2:3], off
	v_or_b32_e32 v2, s46, v193
	v_mad_i64_i32 v[2:3], s[22:23], v2, s40, v[6:7]
	v_lshl_add_u64 v[2:3], v[2:3], 0, s[2:3]
	v_mov_b32_e32 v87, v75
	v_or_b32_e32 v4, s46, v108
	v_lshl_add_u64 v[2:3], v[2:3], 0, v[86:87]
	v_mad_i64_i32 v[4:5], s[22:23], v4, s40, v[6:7]
	v_add_co_u32_e32 v2, vcc, s41, v2
	v_lshl_add_u64 v[4:5], v[4:5], 0, s[2:3]
	s_nop 0
	v_addc_co_u32_e32 v3, vcc, 0, v3, vcc
	v_lshl_add_u64 v[4:5], v[4:5], 0, v[86:87]
	v_add_co_u32_e32 v4, vcc, s41, v4
	v_mov_b32_e32 v89, v75
	s_nop 0
	v_addc_co_u32_e32 v5, vcc, 0, v5, vcc
	global_load_dwordx4 v[42:45], v[2:3], off offset:2048
	global_load_dwordx4 v[50:53], v[4:5], off offset:2048
	v_or_b32_e32 v2, s46, v109
	v_mad_i64_i32 v[2:3], s[22:23], v2, s40, v[6:7]
	v_lshl_add_u64 v[2:3], v[2:3], 0, s[2:3]
	v_or_b32_e32 v4, s46, v110
	v_lshl_add_u64 v[2:3], v[2:3], 0, v[86:87]
	v_mad_i64_i32 v[4:5], s[22:23], v4, s40, v[6:7]
	v_add_co_u32_e32 v2, vcc, s41, v2
	v_lshl_add_u64 v[4:5], v[4:5], 0, s[2:3]
	s_nop 0
	v_addc_co_u32_e32 v3, vcc, 0, v3, vcc
	v_lshl_add_u64 v[4:5], v[4:5], 0, v[86:87]
	v_add_co_u32_e32 v4, vcc, s41, v4
	v_or_b32_e32 v87, s46, v111
	s_nop 0
	v_addc_co_u32_e32 v5, vcc, 0, v5, vcc
	global_load_dwordx4 v[62:65], v[2:3], off offset:2048
	global_load_dwordx4 v[66:69], v[4:5], off offset:2048
	v_lshl_add_u64 v[2:3], v[82:83], 0, v[80:81]
	v_lshl_add_u64 v[4:5], v[82:83], 0, v[84:85]
	global_load_dwordx4 v[34:37], v[2:3], off offset:-128
	global_load_dwordx4 v[26:29], v[2:3], off offset:-64
	global_load_dwordx4 v[38:41], v[4:5], off offset:-128
	global_load_dwordx4 v[30:33], v[4:5], off offset:-64
	global_load_dwordx4 v[18:21], v[2:3], off
	global_load_dwordx4 v[14:17], v[2:3], off offset:64
	global_load_dwordx4 v[22:25], v[4:5], off
	global_load_dwordx4 v[10:13], v[4:5], off offset:64
	v_mad_i64_i32 v[2:3], s[22:23], v87, s40, v[6:7]
	v_lshl_add_u64 v[2:3], v[2:3], 0, s[2:3]
	v_lshl_add_u64 v[2:3], v[2:3], 0, v[88:89]
	s_lshl_b32 s22, s47, 10
	s_mov_b32 s23, s3
	v_lshl_add_u64 v[90:91], v[2:3], 0, s[26:27]
	v_add_co_u32_e32 v92, vcc, s42, v2
	v_or_b32_e32 v2, 16, v87
	v_lshl_add_u64 v[4:5], v[78:79], 0, s[22:23]
	v_addc_co_u32_e32 v93, vcc, 0, v3, vcc
	v_mad_i64_i32 v[2:3], s[22:23], v2, s40, v[6:7]
	v_lshl_add_u64 v[2:3], v[2:3], 0, s[2:3]
	v_lshl_add_u64 v[2:3], v[2:3], 0, v[88:89]
	v_lshl_add_u64 v[94:95], v[2:3], 0, s[26:27]
	v_add_co_u32_e32 v96, vcc, s42, v2
	v_or_b32_e32 v2, 32, v87
	s_nop 0
	v_addc_co_u32_e32 v97, vcc, 0, v3, vcc
	v_mad_i64_i32 v[2:3], s[22:23], v2, s40, v[6:7]
	v_lshl_add_u64 v[2:3], v[2:3], 0, s[2:3]
	v_lshl_add_u64 v[2:3], v[2:3], 0, v[88:89]
	v_lshl_add_u64 v[158:159], v[2:3], 0, s[26:27]
	v_add_co_u32_e32 v160, vcc, s42, v2
	v_or_b32_e32 v2, 48, v87
	s_nop 0
	v_addc_co_u32_e32 v161, vcc, 0, v3, vcc
	v_mad_i64_i32 v[2:3], s[22:23], v2, s40, v[6:7]
	v_lshl_add_u64 v[2:3], v[2:3], 0, s[2:3]
	v_lshl_add_u64 v[2:3], v[2:3], 0, v[88:89]
	v_add_co_u32_e32 v164, vcc, s42, v2
	s_waitcnt vmcnt(16)
	v_mul_f32_e32 v89, 0x3fb8aa3b, v154
	v_mul_f32_e32 v141, 0x3fb8aa3b, v155
	v_lshl_add_u64 v[162:163], v[2:3], 0, s[26:27]
	v_addc_co_u32_e32 v165, vcc, 0, v3, vcc
	global_load_dwordx4 v[6:9], v[4:5], off
	s_nop 0
	global_load_dwordx4 v[2:5], v[4:5], off offset:64
	s_nop 0
	global_load_dwordx2 v[104:105], v[92:93], off
	global_load_dwordx2 v[100:101], v[96:97], off
	global_load_dwordx2 v[98:99], v[94:95], off offset:32
	global_load_dwordx2 v[102:103], v[90:91], off offset:32
	s_nop 0
	global_load_dwordx2 v[96:97], v[160:161], off
	global_load_dwordx2 v[92:93], v[164:165], off
	global_load_dwordx2 v[90:91], v[162:163], off offset:32
	global_load_dwordx2 v[94:95], v[158:159], off offset:32
	v_exp_f32_e32 v158, v89
	v_mul_f32_e32 v89, 0xbfb8aa3b, v154
	v_exp_f32_e32 v159, v141
	v_exp_f32_e32 v154, v89
	v_mul_f32_e32 v89, 0xbfb8aa3b, v155
	v_exp_f32_e32 v155, v89
	v_lshlrev_b32_e32 v160, 16, v142
	v_and_b32_e32 v161, 0xffff0000, v142
	v_pk_mul_f32 v[158:159], v[158:159], s[28:29] op_sel_hi:[1,0]
	v_mul_f32_e32 v89, 0x3fb8aa3b, v156
	v_pk_mul_f32 v[158:159], v[158:159], v[160:161]
	v_lshlrev_b32_e32 v160, 16, v146
	v_and_b32_e32 v161, 0xffff0000, v146
	v_pk_mul_f32 v[154:155], v[154:155], v[160:161]
	v_exp_f32_e32 v160, v89
	v_mul_f32_e32 v89, 0xbfb8aa3b, v156
	v_exp_f32_e32 v142, v89
	v_mul_f32_e32 v89, 0xbfb8aa3b, v157
	v_lshlrev_b32_e32 v162, 16, v143
	v_and_b32_e32 v163, 0xffff0000, v143
	v_exp_f32_e32 v143, v89
	v_mul_f32_e32 v141, 0x3fb8aa3b, v157
	v_exp_f32_e32 v161, v141
	v_lshlrev_b32_e32 v146, 16, v147
	v_and_b32_e32 v147, 0xffff0000, v147
	v_mul_f32_e32 v89, 0x3fb8aa3b, v150
	v_mul_f32_e32 v141, 0x3fb8aa3b, v151
	v_pk_mul_f32 v[146:147], v[142:143], v[146:147]
	v_exp_f32_e32 v142, v89
	v_mul_f32_e32 v89, 0xbfb8aa3b, v150
	v_exp_f32_e32 v143, v141
	v_exp_f32_e32 v150, v89
	v_mul_f32_e32 v89, 0xbfb8aa3b, v151
	v_exp_f32_e32 v151, v89
	v_pk_mul_f32 v[160:161], v[160:161], s[28:29] op_sel_hi:[1,0]
	v_pk_mul_f32 v[142:143], v[142:143], s[28:29] op_sel_hi:[1,0]
	v_pk_mul_f32 v[156:157], v[160:161], v[162:163]
	v_lshlrev_b32_e32 v160, 16, v144
	v_and_b32_e32 v161, 0xffff0000, v144
	v_pk_mul_f32 v[160:161], v[142:143], v[160:161]
	v_lshlrev_b32_e32 v142, 16, v148
	v_and_b32_e32 v143, 0xffff0000, v148
	v_mul_f32_e32 v89, 0x3fb8aa3b, v152
	v_mul_f32_e32 v141, 0x3fb8aa3b, v153
	v_pk_mul_f32 v[150:151], v[150:151], v[142:143]
	v_exp_f32_e32 v142, v89
	v_mul_f32_e32 v89, 0xbfb8aa3b, v152
	v_exp_f32_e32 v143, v141
	v_exp_f32_e32 v144, v89
	v_mul_f32_e32 v89, 0xbfb8aa3b, v153
	v_lshlrev_b32_e32 v162, 16, v145
	v_and_b32_e32 v163, 0xffff0000, v145
	v_exp_f32_e32 v145, v89
	v_pk_mul_f32 v[142:143], v[142:143], s[28:29] op_sel_hi:[1,0]
	s_waitcnt vmcnt(22)
	v_mul_f32_e32 v89, 0x3fb8aa3b, v70
	v_pk_mul_f32 v[152:153], v[142:143], v[162:163]
	v_lshlrev_b32_e32 v142, 16, v149
	v_and_b32_e32 v143, 0xffff0000, v149
	v_pk_mul_f32 v[148:149], v[144:145], v[142:143]
	v_cvt_pk_bf16_f32 v142, v158, v159
	v_cvt_pk_bf16_f32 v143, v156, v157
	v_cvt_pk_bf16_f32 v144, v160, v161
	v_cvt_pk_bf16_f32 v145, v152, v153
	ds_write_b128 v112, v[142:145]
	v_cvt_pk_bf16_f32 v142, v154, v155
	v_cvt_pk_bf16_f32 v143, v146, v147
	v_cvt_pk_bf16_f32 v144, v150, v151
	v_cvt_pk_bf16_f32 v145, v148, v149
	ds_write_b128 v112, v[142:145] offset:17408
	v_exp_f32_e32 v142, v89
	v_mul_f32_e32 v89, 0x3fb8aa3b, v71
	v_exp_f32_e32 v143, v89
	v_mul_f32_e32 v70, 0xbfb8aa3b, v70
	v_lshlrev_b32_e32 v144, 16, v58
	v_and_b32_e32 v145, 0xffff0000, v58
	v_mul_f32_e32 v58, 0xbfb8aa3b, v71
	v_exp_f32_e32 v70, v70
	v_exp_f32_e32 v71, v58
	v_pk_mul_f32 v[142:143], v[142:143], s[28:29] op_sel_hi:[1,0]
	v_mul_f32_e32 v58, 0x3fb8aa3b, v73
	v_pk_mul_f32 v[142:143], v[142:143], v[144:145]
	v_lshlrev_b32_e32 v144, 16, v46
	v_and_b32_e32 v145, 0xffff0000, v46
	v_mul_f32_e32 v46, 0x3fb8aa3b, v72
	v_pk_mul_f32 v[70:71], v[70:71], v[144:145]
	v_exp_f32_e32 v144, v46
	v_mul_f32_e32 v46, 0xbfb8aa3b, v72
	v_exp_f32_e32 v145, v58
	v_exp_f32_e32 v58, v46
	v_mul_f32_e32 v46, 0xbfb8aa3b, v73
	v_lshlrev_b32_e32 v146, 16, v59
	v_and_b32_e32 v147, 0xffff0000, v59
	v_exp_f32_e32 v59, v46
	v_lshlrev_b32_e32 v46, 16, v47
	v_and_b32_e32 v47, 0xffff0000, v47
	v_pk_mul_f32 v[144:145], v[144:145], s[28:29] op_sel_hi:[1,0]
	v_pk_mul_f32 v[58:59], v[58:59], v[46:47]
	v_mul_f32_e32 v46, 0x3fb8aa3b, v54
	v_mul_f32_e32 v47, 0x3fb8aa3b, v55
	v_exp_f32_e32 v46, v46
	v_exp_f32_e32 v47, v47
	v_mul_f32_e32 v54, 0xbfb8aa3b, v54
	v_mul_f32_e32 v55, 0xbfb8aa3b, v55
	v_exp_f32_e32 v54, v54
	v_exp_f32_e32 v55, v55
	v_pk_mul_f32 v[72:73], v[144:145], v[146:147]
	v_lshlrev_b32_e32 v144, 16, v60
	v_and_b32_e32 v145, 0xffff0000, v60
	v_pk_mul_f32 v[46:47], v[46:47], s[28:29] op_sel_hi:[1,0]
	v_lshlrev_b32_e32 v60, 16, v61
	v_pk_mul_f32 v[144:145], v[46:47], v[144:145]
	v_lshlrev_b32_e32 v46, 16, v48
	v_and_b32_e32 v47, 0xffff0000, v48
	v_pk_mul_f32 v[54:55], v[54:55], v[46:47]
	v_mul_f32_e32 v46, 0x3fb8aa3b, v56
	v_mul_f32_e32 v47, 0x3fb8aa3b, v57
	v_exp_f32_e32 v46, v46
	v_mul_f32_e32 v48, 0xbfb8aa3b, v56
	v_exp_f32_e32 v47, v47
	v_exp_f32_e32 v56, v48
	v_mul_f32_e32 v48, 0xbfb8aa3b, v57
	v_exp_f32_e32 v57, v48
	v_and_b32_e32 v61, 0xffff0000, v61
	v_pk_mul_f32 v[46:47], v[46:47], s[28:29] op_sel_hi:[1,0]
	v_cvt_pk_bf16_f32 v48, v144, v145
	v_pk_mul_f32 v[60:61], v[46:47], v[60:61]
	v_lshlrev_b32_e32 v46, 16, v49
	v_and_b32_e32 v47, 0xffff0000, v49
	v_pk_mul_f32 v[56:57], v[56:57], v[46:47]
	v_cvt_pk_bf16_f32 v46, v142, v143
	v_cvt_pk_bf16_f32 v47, v72, v73
	v_cvt_pk_bf16_f32 v49, v60, v61
	ds_write_b128 v113, v[46:49]
	v_cvt_pk_bf16_f32 v46, v70, v71
	v_cvt_pk_bf16_f32 v47, v58, v59
	v_cvt_pk_bf16_f32 v48, v54, v55
	v_cvt_pk_bf16_f32 v49, v56, v57
	ds_write_b128 v113, v[46:49] offset:17408
	s_waitcnt vmcnt(21)
	ds_write_b128 v128, v[42:45] offset:34816
	s_waitcnt vmcnt(20)
	ds_write_b128 v129, v[50:53] offset:34816
	s_waitcnt vmcnt(19)
	ds_write_b128 v128, v[62:65] offset:51712
	s_waitcnt vmcnt(18)
	ds_write_b128 v130, v[66:69] offset:34816
	s_waitcnt lgkmcnt(0)
	s_barrier
	ds_read_b128 v[42:45], v131
	ds_read_b128 v[46:49], v132 offset:17408
	ds_read_b128 v[50:53], v131 offset:64
	ds_read_b128 v[54:57], v132 offset:17472
	s_waitcnt lgkmcnt(2)
	v_mfma_f32_16x16x32_bf16 v[46:49], v[42:45], v[46:49], 0
	ds_read_b128 v[58:61], v132 offset:21760
	ds_read_b128 v[62:65], v132 offset:21824
	s_waitcnt lgkmcnt(2)
	v_mfma_f32_16x16x32_bf16 v[46:49], v[50:53], v[54:57], v[46:49]
	ds_read_b128 v[54:57], v131 offset:128
	s_waitcnt lgkmcnt(2)
	v_mfma_f32_16x16x32_bf16 v[42:45], v[42:45], v[58:61], 0
	s_waitcnt lgkmcnt(1)
	v_mfma_f32_16x16x32_bf16 v[42:45], v[50:53], v[62:65], v[42:45]
	ds_read_b128 v[50:53], v132 offset:17536
	ds_read_b128 v[58:61], v131 offset:192
	ds_read_b128 v[62:65], v132 offset:17600
	s_waitcnt lgkmcnt(2)
	v_mfma_f32_16x16x32_bf16 v[46:49], v[54:57], v[50:53], v[46:49]
	ds_read_b128 v[50:53], v132 offset:21888
	ds_read_b128 v[66:69], v132 offset:21952
	s_waitcnt lgkmcnt(2)
	v_mfma_f32_16x16x32_bf16 v[46:49], v[58:61], v[62:65], v[46:49]
	s_waitcnt lgkmcnt(1)
	v_mfma_f32_16x16x32_bf16 v[42:45], v[54:57], v[50:53], v[42:45]
	s_waitcnt lgkmcnt(0)
	v_mfma_f32_16x16x32_bf16 v[42:45], v[58:61], v[66:69], v[42:45]
	s_nop 3
	v_cndmask_b32_e64 v46, v46, 0, s[4:5]
	v_bfe_u32 v50, v46, 16, 1
	v_add3_u32 v46, v46, v50, s43
	ds_write_b16_d16_hi v133, v46
	v_cndmask_b32_e64 v46, v47, 0, s[6:7]
	v_bfe_u32 v47, v46, 16, 1
	v_add3_u32 v46, v46, v47, s43
	ds_write_b16_d16_hi v133, v46 offset:144
	v_cndmask_b32_e64 v46, v48, 0, s[8:9]
	v_bfe_u32 v47, v46, 16, 1
	v_add3_u32 v46, v46, v47, s43
	ds_write_b16_d16_hi v133, v46 offset:288
	v_cndmask_b32_e64 v46, v49, 0, s[10:11]
	v_bfe_u32 v47, v46, 16, 1
	v_add3_u32 v46, v46, v47, s43
	v_cndmask_b32_e64 v42, v42, 0, s[12:13]
	ds_write_b16_d16_hi v133, v46 offset:432
	v_bfe_u32 v46, v42, 16, 1
	v_add3_u32 v42, v42, v46, s43
	ds_write_b16_d16_hi v114, v42
	v_cndmask_b32_e64 v42, v43, 0, s[14:15]
	v_bfe_u32 v43, v42, 16, 1
	v_add3_u32 v42, v42, v43, s43
	ds_write_b16_d16_hi v115, v42
	v_cndmask_b32_e64 v42, v44, 0, s[16:17]
	v_bfe_u32 v43, v42, 16, 1
	v_add3_u32 v42, v42, v43, s43
	ds_write_b16_d16_hi v116, v42
	v_cndmask_b32_e64 v42, v45, 0, s[18:19]
	v_bfe_u32 v43, v42, 16, 1
	v_add3_u32 v42, v42, v43, s43
	ds_write_b16_d16_hi v117, v42
	s_waitcnt lgkmcnt(0)
	s_barrier
	ds_read_b128 v[42:45], v134
	ds_read_b128 v[46:49], v134 offset:64
	ds_read_b128 v[54:57], v134 offset:4352
	ds_read_b128 v[58:61], v134 offset:4416
	ds_read_b128 v[66:69], v134 offset:8704
	ds_read_b128 v[70:73], v134 offset:8768
	ds_read_b128 v[146:149], v134 offset:13056
	ds_read_b128 v[150:153], v134 offset:13120
	s_waitcnt vmcnt(17) lgkmcnt(7)
	v_mfma_f32_16x16x32_bf16 v[50:53], v[34:37], v[42:45], 0
	s_waitcnt vmcnt(15)
	v_mfma_f32_16x16x32_bf16 v[42:45], v[38:41], v[42:45], 0
	s_waitcnt lgkmcnt(5)
	v_mfma_f32_16x16x32_bf16 v[62:65], v[34:37], v[54:57], 0
	v_mfma_f32_16x16x32_bf16 v[54:57], v[38:41], v[54:57], 0
	s_waitcnt lgkmcnt(3)
	v_mfma_f32_16x16x32_bf16 v[142:145], v[34:37], v[66:69], 0
	v_mfma_f32_16x16x32_bf16 v[66:69], v[38:41], v[66:69], 0
	s_waitcnt lgkmcnt(1)
	v_mfma_f32_16x16x32_bf16 v[34:37], v[34:37], v[146:149], 0
	v_mfma_f32_16x16x32_bf16 v[38:41], v[38:41], v[146:149], 0
	v_mfma_f32_16x16x32_bf16 v[50:53], v[26:29], v[46:49], v[50:53]
	s_waitcnt vmcnt(14)
	v_mfma_f32_16x16x32_bf16 v[42:45], v[30:33], v[46:49], v[42:45]
	v_mfma_f32_16x16x32_bf16 v[46:49], v[26:29], v[58:61], v[62:65]
	v_mfma_f32_16x16x32_bf16 v[54:57], v[30:33], v[58:61], v[54:57]
	v_mfma_f32_16x16x32_bf16 v[58:61], v[26:29], v[70:73], v[142:145]
	v_mfma_f32_16x16x32_bf16 v[62:65], v[30:33], v[70:73], v[66:69]
	s_waitcnt lgkmcnt(0)
	v_mfma_f32_16x16x32_bf16 v[26:29], v[26:29], v[150:153], v[34:37]
	v_mfma_f32_16x16x32_bf16 v[30:33], v[30:33], v[150:153], v[38:41]
	s_nop 1
	ds_read_b128 v[34:37], v134 offset:128
	ds_read_b128 v[38:41], v134 offset:192
	s_waitcnt vmcnt(13) lgkmcnt(1)
	v_mfma_f32_16x16x32_bf16 v[50:53], v[18:21], v[34:37], v[50:53]
	s_waitcnt vmcnt(11)
	v_mfma_f32_16x16x32_bf16 v[34:37], v[22:25], v[34:37], v[42:45]
	s_nop 2
	ds_read_b128 v[42:45], v134 offset:4480
	ds_read_b128 v[66:69], v134 offset:4544
	s_waitcnt lgkmcnt(1)
	v_mfma_f32_16x16x32_bf16 v[46:49], v[18:21], v[42:45], v[46:49]
	v_mfma_f32_16x16x32_bf16 v[42:45], v[22:25], v[42:45], v[54:57]
	s_nop 2
	ds_read_b128 v[54:57], v134 offset:8832
	ds_read_b128 v[70:73], v134 offset:8896
	s_waitcnt lgkmcnt(1)
	v_mfma_f32_16x16x32_bf16 v[58:61], v[18:21], v[54:57], v[58:61]
	v_mfma_f32_16x16x32_bf16 v[54:57], v[22:25], v[54:57], v[62:65]
	s_nop 2
	ds_read_b128 v[62:65], v134 offset:13184
	ds_read_b128 v[142:145], v134 offset:13248
	s_waitcnt lgkmcnt(1)
	v_mfma_f32_16x16x32_bf16 v[18:21], v[18:21], v[62:65], v[26:29]
	v_mfma_f32_16x16x32_bf16 v[22:25], v[22:25], v[62:65], v[30:33]
	v_mfma_f32_16x16x32_bf16 v[26:29], v[14:17], v[38:41], v[50:53]
	s_waitcnt vmcnt(10)
	v_mfma_f32_16x16x32_bf16 v[30:33], v[10:13], v[38:41], v[34:37]
	v_mfma_f32_16x16x32_bf16 v[34:37], v[14:17], v[66:69], v[46:49]
	v_mfma_f32_16x16x32_bf16 v[38:41], v[10:13], v[66:69], v[42:45]
	v_mfma_f32_16x16x32_bf16 v[42:45], v[14:17], v[70:73], v[58:61]
	s_waitcnt lgkmcnt(0)
	v_mfma_f32_16x16x32_bf16 v[14:17], v[14:17], v[142:145], v[18:21]
	s_nop 2
	ds_read_b64_tr_b16 v[20:21], v135 offset:36928
	ds_read_b64_tr_b16 v[18:19], v135 offset:34816
	v_mfma_f32_16x16x32_bf16 v[46:49], v[10:13], v[70:73], v[54:57]
	v_mfma_f32_16x16x32_bf16 v[10:13], v[10:13], v[142:145], v[22:25]
	s_nop 2
	ds_read_b64_tr_b16 v[24:25], v135 offset:36960
	ds_read_b64_tr_b16 v[22:23], v135 offset:34848
	ds_read_b128 v[50:53], v136
	ds_read_b128 v[54:57], v136 offset:64
	s_waitcnt lgkmcnt(1)
	v_mfma_f32_16x16x32_bf16 v[26:29], v[18:21], v[50:53], v[26:29]
	v_mfma_f32_16x16x32_bf16 v[30:33], v[22:25], v[50:53], v[30:33]
	ds_read_b128 v[50:53], v136 offset:2304
	ds_read_b128 v[58:61], v136 offset:2368
	s_waitcnt lgkmcnt(1)
	v_mfma_f32_16x16x32_bf16 v[62:65], v[18:21], v[50:53], v[34:37]
	s_nop 2
	ds_read_b128 v[34:37], v136 offset:4608
	ds_read_b128 v[66:69], v136 offset:4672
	s_waitcnt lgkmcnt(1)
	v_mfma_f32_16x16x32_bf16 v[42:45], v[18:21], v[34:37], v[42:45]
	v_mfma_f32_16x16x32_bf16 v[46:49], v[22:25], v[34:37], v[46:49]
	ds_read_b128 v[34:37], v136 offset:6912
	ds_read_b128 v[70:73], v136 offset:6976
	ds_read_b64_tr_b16 v[142:143], v135 offset:51712
	ds_read_b64_tr_b16 v[144:145], v135 offset:53824
	ds_read_b64_tr_b16 v[152:153], v135 offset:53856
	ds_read_b64_tr_b16 v[150:151], v135 offset:51744
	s_waitcnt lgkmcnt(5)
	v_mfma_f32_16x16x32_bf16 v[14:17], v[18:21], v[34:37], v[14:17]
	v_mfma_f32_16x16x32_bf16 v[50:53], v[22:25], v[50:53], v[38:41]
	v_mfma_f32_16x16x32_bf16 v[146:149], v[22:25], v[34:37], v[10:13]
	s_waitcnt lgkmcnt(2)
	v_mfma_f32_16x16x32_bf16 v[38:41], v[142:145], v[54:57], v[26:29]
	v_mfma_f32_16x16x32_bf16 v[10:13], v[142:145], v[70:73], v[14:17]
	s_nop 2
	v_and_b32_e32 v15, 64, v139
	v_xor_b32_e32 v14, 16, v139
	v_add_u32_e32 v15, 64, v15
	v_cmp_lt_i32_e32 vcc, v14, v15
	s_waitcnt lgkmcnt(0)
	v_mfma_f32_16x16x32_bf16 v[34:37], v[150:153], v[54:57], v[30:33]
	v_xor_b32_e32 v17, 32, v139
	v_cndmask_b32_e32 v14, v139, v14, vcc
	v_cmp_lt_i32_e32 vcc, v17, v15
	v_mfma_f32_16x16x32_bf16 v[22:25], v[142:145], v[66:69], v[42:45]
	s_nop 0
	v_cndmask_b32_e32 v15, v139, v17, vcc
	s_nop 0
	v_lshlrev_b32_e32 v42, 2, v14
	v_mul_f32_e32 v14, v39, v39
	v_fmac_f32_e32 v14, v38, v38
	v_fmac_f32_e32 v14, v40, v40
	v_fmac_f32_e32 v14, v41, v41
	v_fmac_f32_e32 v14, v34, v34
	v_fmac_f32_e32 v14, v35, v35
	v_fmac_f32_e32 v14, v36, v36
	v_fmac_f32_e32 v14, v37, v37
	ds_bpermute_b32 v16, v42, v14
	v_lshlrev_b32_e32 v43, 2, v15
	v_mfma_f32_16x16x32_bf16 v[30:33], v[142:145], v[58:61], v[62:65]
	s_waitcnt lgkmcnt(0)
	v_add_f32_e32 v44, v14, v16
	ds_bpermute_b32 v45, v43, v44
	v_mfma_f32_16x16x32_bf16 v[26:29], v[150:153], v[58:61], v[50:53]
	v_mfma_f32_16x16x32_bf16 v[18:21], v[150:153], v[66:69], v[46:49]
	v_mfma_f32_16x16x32_bf16 v[14:17], v[150:153], v[70:73], v[146:149]
	s_and_saveexec_b64 s[22:23], s[20:21]
	s_cbranch_execz .LBB0_1360
	s_waitcnt lgkmcnt(0)
	v_add_f32_e32 v44, v44, v45
	ds_write_b32 v140, v44

.LBB0_1368:
	s_and_b32 s14, s29, 3
	s_lshl_b32 s4, 0xffffffc0, s14
	v_add_u32_e32 v2, s4, v104
	s_and_b32 s10, s19, 0xffffff80
	s_lshl_b32 s30, s29, 5
	s_lshl_b32 s2, s14, 9
	v_lshrrev_b32_e32 v2, 5, v2
	s_and_b32 s11, s30, 0xfffff000
	s_lshl_b32 s31, s14, 8
	v_lshl_add_u64 v[6:7], v[78:79], 0, s[2:3]
	v_add3_u32 v8, v2, s10, -15
	v_lshl_add_u32 v9, v2, 9, v107
	v_add_u32_e32 v10, s4, v0
	s_mov_b64 s[4:5], 0
	s_nop 0
	s_barrier
	s_branch .LBB0_1370

.LBB0_1405:
	v_readlane_b32 s0, v249, 34
	v_readlane_b32 s1, v249, 35
	s_cmpk_lg_i32 s0, 0x100
	s_mov_b64 s[0:1], -1
	v_writelane_b32 v249, s76, 48
	s_nop 0
	s_barrier
	v_writelane_b32 v249, s77, 49
	s_cbranch_scc0 .LBB0_1420
	s_cmpk_gt_i32 s76, 0x3ff
	v_writelane_b32 v249, s75, 50
	s_cbranch_scc1 .LBB0_1419
	v_mbcnt_lo_u32_b32 v2, -1, 0
	v_mbcnt_hi_u32_b32 v2, -1, v2
	v_and_b32_e32 v4, 64, v2
	v_xor_b32_e32 v3, 16, v2
	v_add_u32_e32 v4, 64, v4
	v_cmp_lt_i32_e32 vcc, v3, v4
	v_readlane_b32 s43, v249, 45
	s_mul_i32 s0, s43, 0x1500
	v_cndmask_b32_e32 v3, v2, v3, vcc
	v_lshlrev_b32_e32 v39, 2, v3
	v_xor_b32_e32 v3, 32, v2
	s_add_i32 s42, s0, 0
	v_cmp_lt_i32_e32 vcc, v3, v4
	s_add_i32 s42, s42, 0x17a00
	s_lshl_b32 s33, s43, 4
	v_cndmask_b32_e32 v2, v2, v3, vcc
	s_add_u32 s2, s92, 0x3a000000
	s_movk_i32 s0, 0x200
	v_lshrrev_b32_e32 v3, 1, v0
	s_addc_u32 s3, s93, 0
	v_cmp_gt_u32_e64 s[4:5], s0, v0
	v_and_b32_e32 v14, 15, v0
	v_and_b32_e32 v15, 24, v3
	s_add_u32 s44, s92, 0x100000
	v_writelane_b32 v249, s4, 0
	v_or_b32_e32 v45, s33, v14
	s_movk_i32 s0, 0x90
	v_lshlrev_b32_e32 v16, 1, v15
	v_lshlrev_b32_e32 v44, 2, v2
	s_addc_u32 s45, s93, 0
	v_writelane_b32 v249, s5, 1
	v_mul_lo_u32 v2, v45, s0
	v_add_u32_e32 v3, 0, v16
	s_add_i32 s4, s33, 16
	v_add_u32_e32 v46, v3, v2
	v_or_b32_e32 v2, s4, v14
	s_add_i32 s5, s33, 32
	v_mul_lo_u32 v4, v2, s0
	v_or_b32_e32 v2, s5, v14
	s_add_i32 s16, s33, 48
	v_mul_lo_u32 v5, v2, s0
	v_or_b32_e32 v2, s16, v14
	s_add_i32 s18, s33, 64
	v_mul_lo_u32 v6, v2, s0
	v_or_b32_e32 v2, s18, v14
	s_add_i32 s20, s33, 0x50
	v_mul_lo_u32 v7, v2, s0
	v_or_b32_e32 v2, s20, v14
	s_add_i32 s22, s33, 0x60
	v_mul_lo_u32 v8, v2, s0
	v_or_b32_e32 v2, s22, v14
	s_add_i32 s24, s33, 0x70
	v_mul_lo_u32 v9, v2, s0
	v_or_b32_e32 v2, s24, v14
	s_add_i32 s26, s33, 0x80
	v_mul_lo_u32 v10, v2, s0
	v_or_b32_e32 v2, s26, v14
	s_add_i32 s34, s33, 0x90
	v_mul_lo_u32 v11, v2, s0
	v_or_b32_e32 v2, s34, v14
	v_mul_lo_u32 v12, v2, s0
	v_lshrrev_b32_e32 v2, 2, v178
	v_and_b32_e32 v2, 12, v2
	v_add_u32_e32 v17, 0x80, v45
	v_or_b32_e32 v18, s33, v2
	v_cmp_gt_u32_e32 vcc, v2, v14
	v_cmp_le_u32_e64 s[8:9], v18, v17
	s_and_b64 s[8:9], vcc, s[8:9]
	v_cmp_ge_u32_e32 vcc, v2, v14
	v_writelane_b32 v249, s8, 55
	s_movk_i32 s25, 0x7e
	v_or_b32_e32 v19, 2, v18
	v_writelane_b32 v249, s9, 56
	v_cmp_le_u32_e64 s[10:11], v19, v17
	v_readlane_b32 s27, v249, 50
	s_cmpk_gt_u32 s27, 0x1ff
	s_cselect_b64 s[8:9], -1, 0
	v_writelane_b32 v249, s8, 57
	v_and_b32_e32 v13, 3, v0
	v_lshlrev_b32_e32 v38, 4, v13
	v_writelane_b32 v249, s9, 58
	v_cmp_lt_u32_e64 s[8:9], v18, v17
	s_and_b64 s[8:9], vcc, s[8:9]
	v_cmp_gt_u32_e32 vcc, v19, v45
	v_writelane_b32 v249, s8, 59
	v_cmp_eq_u32_e64 s[6:7], 0, v13
	v_lshl_add_u32 v13, v13, 5, 0
	v_writelane_b32 v249, s9, 60
	v_cmp_lt_u32_e64 s[8:9], s25, v18
	v_or_b32_e32 v18, 3, v18
	v_mad_u32_u24 v53, v1, s0, 0
	v_writelane_b32 v249, s8, 61
	s_mov_b32 s1, 0
	v_mov_b32_e32 v41, 0
	v_writelane_b32 v249, s9, 62
	s_and_b64 s[8:9], vcc, s[10:11]
	v_writelane_b32 v249, s8, 63
	v_cmp_gt_u32_e32 vcc, v18, v45
	v_cmp_le_u32_e64 s[10:11], v18, v17
	v_writelane_b32 v248, s9, 0
	s_and_b64 s[8:9], vcc, s[10:11]
	v_or_b32_e32 v18, s4, v2
	v_writelane_b32 v248, s8, 1
	v_cmp_gt_u32_e32 vcc, v18, v45
	v_cmp_le_u32_e64 s[10:11], v18, v17
	v_writelane_b32 v248, s9, 2
	s_and_b64 s[8:9], vcc, s[10:11]
	v_writelane_b32 v248, s8, 3
	s_cmpk_gt_u32 s27, 0x1bf
	v_cmp_ge_u32_e32 vcc, v18, v45
	v_writelane_b32 v248, s9, 4
	s_cselect_b64 s[8:9], -1, 0
	v_writelane_b32 v248, s8, 5
	v_cmp_lt_u32_e64 s[10:11], v18, v17
	v_or_b32_e32 v19, 2, v18
	v_writelane_b32 v248, s9, 6
	s_and_b64 s[8:9], vcc, s[10:11]
	v_writelane_b32 v248, s8, 7
	v_cmp_gt_u32_e32 vcc, v19, v45
	v_cmp_le_u32_e64 s[12:13], v19, v17
	v_writelane_b32 v248, s9, 8
	v_cmp_lt_u32_e64 s[8:9], s25, v18
	v_or_b32_e32 v18, 3, v18
	v_or_b32_e32 v54, 0xffffff80, v1
	v_writelane_b32 v248, s8, 9
	s_mov_b32 s80, 0xcc00
	s_mov_b32 s72, 0x3e000000
	v_writelane_b32 v248, s9, 10
	s_and_b64 s[8:9], vcc, s[12:13]
	v_writelane_b32 v248, s8, 11
	v_cmp_gt_u32_e32 vcc, v18, v45
	v_cmp_le_u32_e64 s[12:13], v18, v17
	v_writelane_b32 v248, s9, 12
	s_and_b64 s[8:9], vcc, s[12:13]
	v_or_b32_e32 v18, s5, v2
	v_writelane_b32 v248, s8, 13
	v_cmp_gt_u32_e32 vcc, v18, v45
	v_cmp_le_u32_e64 s[12:13], v18, v17
	v_writelane_b32 v248, s9, 14
	s_and_b64 s[4:5], vcc, s[12:13]
	v_writelane_b32 v248, s4, 15
	s_cmpk_gt_u32 s27, 0x17f
	v_cmp_ge_u32_e32 vcc, v18, v45
	v_writelane_b32 v248, s5, 16
	s_cselect_b64 s[4:5], -1, 0
	v_writelane_b32 v248, s4, 17
	v_cmp_lt_u32_e64 s[12:13], v18, v17
	v_or_b32_e32 v19, 2, v18
	v_writelane_b32 v248, s5, 18
	s_and_b64 s[4:5], vcc, s[12:13]
	v_writelane_b32 v248, s4, 19
	v_cmp_gt_u32_e32 vcc, v19, v45
	v_cmp_le_u32_e64 s[14:15], v19, v17
	v_writelane_b32 v248, s5, 20
	v_cmp_lt_u32_e64 s[4:5], s25, v18
	v_or_b32_e32 v18, 3, v18
	s_movk_i32 s12, 0x150
	v_writelane_b32 v248, s4, 21
	v_add_u32_e32 v56, v3, v4
	v_add_u32_e32 v57, v3, v5
	v_writelane_b32 v248, s5, 22
	s_and_b64 s[4:5], vcc, s[14:15]
	v_writelane_b32 v248, s4, 23
	v_cmp_gt_u32_e32 vcc, v18, v45
	v_cmp_le_u32_e64 s[14:15], v18, v17
	v_writelane_b32 v248, s5, 24
	s_and_b64 s[4:5], vcc, s[14:15]
	v_or_b32_e32 v18, s16, v2
	v_writelane_b32 v249, s4, 51
	v_cmp_gt_u32_e32 vcc, v18, v45
	v_cmp_le_u32_e64 s[14:15], v18, v17
	v_writelane_b32 v249, s5, 52
	s_and_b64 s[4:5], vcc, s[14:15]
	v_writelane_b32 v249, s4, 53
	s_cmpk_gt_u32 s27, 0x13f
	v_cmp_ge_u32_e32 vcc, v18, v45
	v_writelane_b32 v249, s5, 54
	s_cselect_b64 s[4:5], -1, 0
	v_writelane_b32 v248, s4, 25
	v_cmp_lt_u32_e64 s[14:15], v18, v17
	v_or_b32_e32 v19, 2, v18
	v_writelane_b32 v248, s5, 26
	s_and_b64 s[4:5], vcc, s[14:15]
	v_writelane_b32 v248, s4, 27
	v_cmp_gt_u32_e32 vcc, v19, v45
	v_cmp_le_u32_e64 s[16:17], v19, v17
	v_writelane_b32 v248, s5, 28
	v_cmp_lt_u32_e64 s[4:5], s25, v18
	v_or_b32_e32 v18, 3, v18
	v_add_u32_e32 v58, v3, v6
	v_writelane_b32 v248, s4, 29
	v_add_u32_e32 v59, v3, v7
	v_add_u32_e32 v60, v3, v8
	v_writelane_b32 v248, s5, 30
	s_and_b64 s[4:5], vcc, s[16:17]
	v_writelane_b32 v248, s4, 31
	v_cmp_gt_u32_e32 vcc, v18, v45
	v_cmp_le_u32_e64 s[16:17], v18, v17
	v_writelane_b32 v248, s5, 32
	s_and_b64 s[4:5], vcc, s[16:17]
	v_or_b32_e32 v18, s18, v2
	v_writelane_b32 v248, s4, 33
	v_cmp_gt_u32_e32 vcc, v18, v45
	v_cmp_le_u32_e64 s[16:17], v18, v17
	v_writelane_b32 v248, s5, 34
	s_and_b64 s[4:5], vcc, s[16:17]
	v_writelane_b32 v248, s4, 35
	s_cmpk_gt_u32 s27, 0xff
	v_cmp_ge_u32_e32 vcc, v18, v45
	v_writelane_b32 v248, s5, 36
	s_cselect_b64 s[4:5], -1, 0
	v_writelane_b32 v248, s4, 37
	v_cmp_lt_u32_e64 s[16:17], v18, v17
	v_or_b32_e32 v19, 2, v18
	v_writelane_b32 v248, s5, 38
	s_and_b64 s[4:5], vcc, s[16:17]
	v_writelane_b32 v248, s4, 39
	v_cmp_gt_u32_e32 vcc, v19, v45
	v_cmp_le_u32_e64 s[18:19], v19, v17
	v_writelane_b32 v248, s5, 40
	v_cmp_lt_u32_e64 s[4:5], s25, v18
	v_or_b32_e32 v18, 3, v18
	v_add_u32_e32 v61, v3, v9
	v_writelane_b32 v248, s4, 41
	v_add_u32_e32 v62, v3, v10
	v_add_u32_e32 v63, v3, v11
	v_writelane_b32 v248, s5, 42
	s_and_b64 s[4:5], vcc, s[18:19]
	v_writelane_b32 v248, s4, 43
	v_cmp_gt_u32_e32 vcc, v18, v45
	v_cmp_le_u32_e64 s[18:19], v18, v17
	v_writelane_b32 v248, s5, 44
	s_and_b64 s[4:5], vcc, s[18:19]
	v_or_b32_e32 v18, s20, v2
	v_writelane_b32 v248, s4, 45
	v_cmp_gt_u32_e32 vcc, v18, v45
	v_cmp_le_u32_e64 s[18:19], v18, v17
	v_writelane_b32 v248, s5, 46
	s_and_b64 s[4:5], vcc, s[18:19]
	v_writelane_b32 v248, s4, 47
	s_cmpk_gt_u32 s27, 0xbf
	v_cmp_ge_u32_e32 vcc, v18, v45
	v_cmp_lt_u32_e64 s[18:19], v18, v17
	v_or_b32_e32 v19, 2, v18
	v_writelane_b32 v248, s5, 48
	s_cselect_b64 s[86:87], -1, 0
	s_and_b64 s[88:89], vcc, s[18:19]
	v_cmp_lt_u32_e64 s[4:5], s25, v18
	v_cmp_gt_u32_e32 vcc, v19, v45
	v_cmp_le_u32_e64 s[20:21], v19, v17
	v_or_b32_e32 v18, 3, v18
	s_and_b64 s[8:9], vcc, s[20:21]
	v_cmp_gt_u32_e32 vcc, v18, v45
	v_cmp_le_u32_e64 s[20:21], v18, v17
	v_or_b32_e32 v18, s22, v2
	s_and_b64 s[90:91], vcc, s[20:21]
	v_cmp_gt_u32_e32 vcc, v18, v45
	v_cmp_le_u32_e64 s[20:21], v18, v17
	s_and_b64 s[16:17], vcc, s[20:21]
	v_writelane_b32 v248, s4, 49
	s_cmpk_gt_u32 s27, 0x7f
	v_cmp_ge_u32_e32 vcc, v18, v45
	v_cmp_lt_u32_e64 s[20:21], v18, v17
	v_or_b32_e32 v19, 2, v18
	v_writelane_b32 v248, s5, 50
	s_cselect_b64 s[96:97], -1, 0
	s_and_b64 s[4:5], vcc, s[20:21]
	v_cmp_lt_u32_e64 s[20:21], s25, v18
	v_cmp_gt_u32_e32 vcc, v19, v45
	v_cmp_le_u32_e64 s[22:23], v19, v17
	v_or_b32_e32 v18, 3, v18
	s_and_b64 s[46:47], vcc, s[22:23]
	v_cmp_gt_u32_e32 vcc, v18, v45
	v_cmp_le_u32_e64 s[22:23], v18, v17
	v_or_b32_e32 v18, s24, v2
	s_and_b64 s[10:11], vcc, s[22:23]
	v_cmp_gt_u32_e32 vcc, v18, v45
	v_cmp_le_u32_e64 s[22:23], v18, v17
	s_and_b64 s[18:19], vcc, s[22:23]
	s_cmp_gt_u32 s27, 63
	v_cmp_ge_u32_e32 vcc, v18, v45
	v_cmp_lt_u32_e64 s[22:23], v18, v17
	v_or_b32_e32 v19, 2, v18
	s_cselect_b64 s[64:65], -1, 0
	s_and_b64 s[66:67], vcc, s[22:23]
	v_cmp_lt_u32_e64 s[22:23], s25, v18
	v_cmp_gt_u32_e32 vcc, v19, v45
	v_cmp_le_u32_e64 s[24:25], v19, v17
	v_or_b32_e32 v18, 3, v18
	s_and_b64 s[68:69], vcc, s[24:25]
	v_cmp_gt_u32_e32 vcc, v18, v45
	v_cmp_le_u32_e64 s[24:25], v18, v17
	v_or_b32_e32 v18, s26, v2
	s_and_b64 s[70:71], vcc, s[24:25]
	v_cmp_gt_u32_e32 vcc, v18, v45
	v_cmp_le_u32_e64 s[24:25], v18, v17
	s_and_b64 s[24:25], vcc, s[24:25]
	v_cmp_ge_u32_e32 vcc, v18, v45
	v_cmp_lt_u32_e64 s[26:27], v18, v17
	v_or_b32_e32 v19, 2, v18
	s_and_b64 s[26:27], vcc, s[26:27]
	v_cmp_gt_u32_e32 vcc, v19, v45
	v_cmp_le_u32_e64 s[28:29], v19, v17
	v_or_b32_e32 v18, 3, v18
	s_and_b64 s[28:29], vcc, s[28:29]
	v_cmp_gt_u32_e32 vcc, v18, v45
	v_cmp_le_u32_e64 s[30:31], v18, v17
	v_or_b32_e32 v18, s34, v2
	s_and_b64 s[30:31], vcc, s[30:31]
	v_cmp_gt_u32_e32 vcc, v18, v45
	v_cmp_le_u32_e64 s[34:35], v18, v17
	s_and_b64 s[34:35], vcc, s[34:35]
	v_cmp_ge_u32_e32 vcc, v18, v45
	v_cmp_lt_u32_e64 s[36:37], v18, v17
	v_or_b32_e32 v19, 2, v18
	s_and_b64 s[36:37], vcc, s[36:37]
	v_cmp_gt_u32_e32 vcc, v19, v45
	v_cmp_le_u32_e64 s[38:39], v19, v17
	v_or_b32_e32 v18, 3, v18
	s_and_b64 s[38:39], vcc, s[38:39]
	v_cmp_gt_u32_e32 vcc, v18, v45
	v_cmp_le_u32_e64 s[40:41], v18, v17
	v_mov_b32_e32 v17, s42
	s_and_b64 s[40:41], vcc, s[40:41]
	v_mad_u32_u24 v14, v14, s12, v17
	v_lshl_add_u32 v47, v2, 1, v14
	v_add_u32_e32 v48, v14, v16
	v_add_u32_e32 v14, s33, v15
	s_add_u32 s12, s92, 0xf000000
	v_and_or_b32 v14, v1, 3, v14
	s_addc_u32 s13, s93, 0
	s_lshl_b32 s14, s43, 11
	v_lshlrev_b32_e32 v15, 1, v195
	v_mul_lo_u32 v14, v14, s0
	s_and_b32 s33, s14, 0x3800
	v_readlane_b32 s14, v249, 48
	v_add3_u32 v49, 0, v15, v14
	v_lshrrev_b32_e32 v14, 1, v178
	v_readlane_b32 s15, v249, 49
	v_mul_u32_u24_e32 v17, 0x90, v1
	v_and_b32_e32 v14, 24, v14
	s_mov_b32 s0, s14
	s_lshl_b32 s78, s14, 3
	v_readlane_b32 s14, v249, 34
	v_add_u32_e32 v50, 0xe100, v49
	v_or_b32_e32 v51, s33, v14
	v_or_b32_e32 v52, 32, v14
	s_or_b32 s73, s33, 0x400
	s_lshl_b32 s79, s14, 3
	v_add_u32_e32 v55, v13, v17
	v_add_u32_e32 v64, v3, v12
	v_lshlrev_b32_e32 v42, 1, v2
	v_mov_b32_e32 v65, 0xff800000
	s_mov_b32 s81, s0
	s_mov_b32 s14, s0
	v_readlane_b32 s15, v249, 35
	s_branch .LBB0_1409
